# cache-shift copy: further 18432 units moved from the FFN-out slots into S5 pass B (T1 accumulators as the buffer between two items); FFN-out slots now 1776 units each
# speedup vs baseline: 1.0180x; 1.0107x over previous
.Lcpy1p_loop:
	s_add_i32 s101, s80, s100
	s_cmp_lt_u32 s101, 0x2474
	s_cbranch_scc0 .Lcpy1p_tail
	s_mul_hi_u32 s81, s80, 0x2ad5802b
	s_lshr_b32 s81, s81, 8
	s_mul_i32 s82, s81, 0x5fa
	s_sub_i32 s82, s80, s82
	s_lshl_b32 s82, s82, 13
	s_and_b32 s83, s81, 31
	s_mul_i32 s83, s83, 0xc00000
	s_add_i32 s82, s82, s83
	s_cmp_lt_u32 s81, 32
	s_cselect_b32 s84, s92, s94
	s_cselect_b32 s85, s93, s95
	s_mov_b32 s83, 0x1f210000
	s_cselect_b32 s83, 0x7210000, s83
	s_add_u32 s84, s84, s82
	s_addc_u32 s85, s85, 0
	s_add_u32 s84, s84, 0xc000
	s_addc_u32 s85, s85, 0
	s_add_u32 s83, s83, s82
	s_add_u32 s86, s98, s83
	s_addc_u32 s87, s99, 0
	s_mul_hi_u32 s81, s101, 0x2ad5802b
	s_lshr_b32 s81, s81, 8
	s_mul_i32 s82, s81, 0x5fa
	s_sub_i32 s82, s101, s82
	s_lshl_b32 s82, s82, 13
	s_and_b32 s83, s81, 31
	s_mul_i32 s83, s83, 0xc00000
	s_add_i32 s82, s82, s83
	s_cmp_lt_u32 s81, 32
	s_cselect_b32 s88, s92, s94
	s_cselect_b32 s89, s93, s95
	s_mov_b32 s83, 0x1f210000
	s_cselect_b32 s83, 0x7210000, s83
	s_add_u32 s88, s88, s82
	s_addc_u32 s89, s89, 0
	s_add_u32 s88, s88, 0xc000
	s_addc_u32 s89, s89, 0
	s_add_u32 s83, s83, s82
	s_add_u32 s90, s98, s83
	s_addc_u32 s91, s99, 0
	global_load_dwordx4 v[64:67], v22, s[84:85] nt
	global_load_dwordx4 v[68:71], v22, s[84:85] offset:1024 nt
	global_load_dwordx4 v[72:75], v22, s[84:85] offset:2048 nt
	global_load_dwordx4 v[76:79], v22, s[84:85] offset:3072 nt
	global_load_dwordx4 v[80:83], v23, s[84:85] nt
	global_load_dwordx4 v[84:87], v23, s[84:85] offset:1024 nt
	global_load_dwordx4 v[88:91], v23, s[84:85] offset:2048 nt
	global_load_dwordx4 v[92:95], v23, s[84:85] offset:3072 nt
	global_load_dwordx4 v[96:99], v22, s[88:89] nt
	global_load_dwordx4 v[100:103], v22, s[88:89] offset:1024 nt
	global_load_dwordx4 v[104:107], v22, s[88:89] offset:2048 nt
	global_load_dwordx4 v[108:111], v22, s[88:89] offset:3072 nt
	global_load_dwordx4 v[112:115], v23, s[88:89] nt
	global_load_dwordx4 v[116:119], v23, s[88:89] offset:1024 nt
	global_load_dwordx4 v[120:123], v23, s[88:89] offset:2048 nt
	global_load_dwordx4 v[124:127], v23, s[88:89] offset:3072 nt
	s_waitcnt vmcnt(15)
	global_store_dwordx4 v22, v[64:67], s[86:87] nt
	s_waitcnt vmcnt(15)
	global_store_dwordx4 v22, v[68:71], s[86:87] offset:1024 nt
	s_waitcnt vmcnt(15)
	global_store_dwordx4 v22, v[72:75], s[86:87] offset:2048 nt
	s_waitcnt vmcnt(15)
	global_store_dwordx4 v22, v[76:79], s[86:87] offset:3072 nt
	s_waitcnt vmcnt(15)
	global_store_dwordx4 v23, v[80:83], s[86:87] nt
	s_waitcnt vmcnt(15)
	global_store_dwordx4 v23, v[84:87], s[86:87] offset:1024 nt
	s_waitcnt vmcnt(15)
	global_store_dwordx4 v23, v[88:91], s[86:87] offset:2048 nt
	s_waitcnt vmcnt(15)
	global_store_dwordx4 v23, v[92:95], s[86:87] offset:3072 nt
	s_waitcnt vmcnt(15)
	global_store_dwordx4 v22, v[96:99], s[90:91] nt
	s_waitcnt vmcnt(15)
	global_store_dwordx4 v22, v[100:103], s[90:91] offset:1024 nt
	s_waitcnt vmcnt(15)
	global_store_dwordx4 v22, v[104:107], s[90:91] offset:2048 nt
	s_waitcnt vmcnt(15)
	global_store_dwordx4 v22, v[108:111], s[90:91] offset:3072 nt
	s_waitcnt vmcnt(15)
	global_store_dwordx4 v23, v[112:115], s[90:91] nt
	s_waitcnt vmcnt(15)
	global_store_dwordx4 v23, v[116:119], s[90:91] offset:1024 nt
	s_waitcnt vmcnt(15)
	global_store_dwordx4 v23, v[120:123], s[90:91] offset:2048 nt
	s_waitcnt vmcnt(15)
	global_store_dwordx4 v23, v[124:127], s[90:91] offset:3072 nt
	s_add_i32 s80, s101, s100
	s_branch .Lcpy1p_loop
.Lcpy1p_tail:
	s_cmp_lt_u32 s80, 0x2474
	s_cbranch_scc0 .Lcpy1p_end
	s_mul_hi_u32 s81, s80, 0x2ad5802b
	s_lshr_b32 s81, s81, 8
	s_mul_i32 s82, s81, 0x5fa
	s_sub_i32 s82, s80, s82
	s_lshl_b32 s82, s82, 13
	s_and_b32 s83, s81, 31
	s_mul_i32 s83, s83, 0xc00000
	s_add_i32 s82, s82, s83
	s_cmp_lt_u32 s81, 32
	s_cselect_b32 s84, s92, s94
	s_cselect_b32 s85, s93, s95
	s_mov_b32 s83, 0x1f210000
	s_cselect_b32 s83, 0x7210000, s83
	s_add_u32 s84, s84, s82
	s_addc_u32 s85, s85, 0
	s_add_u32 s84, s84, 0xc000
	s_addc_u32 s85, s85, 0
	s_add_u32 s83, s83, s82
	s_add_u32 s86, s98, s83
	s_addc_u32 s87, s99, 0
	global_load_dwordx4 v[64:67], v22, s[84:85] nt
	global_load_dwordx4 v[68:71], v22, s[84:85] offset:1024 nt
	global_load_dwordx4 v[72:75], v22, s[84:85] offset:2048 nt
	global_load_dwordx4 v[76:79], v22, s[84:85] offset:3072 nt
	global_load_dwordx4 v[80:83], v23, s[84:85] nt
	global_load_dwordx4 v[84:87], v23, s[84:85] offset:1024 nt
	global_load_dwordx4 v[88:91], v23, s[84:85] offset:2048 nt
	global_load_dwordx4 v[92:95], v23, s[84:85] offset:3072 nt
	s_waitcnt vmcnt(7)
	global_store_dwordx4 v22, v[64:67], s[86:87] nt
	s_waitcnt vmcnt(7)
	global_store_dwordx4 v22, v[68:71], s[86:87] offset:1024 nt
	s_waitcnt vmcnt(7)
	global_store_dwordx4 v22, v[72:75], s[86:87] offset:2048 nt
	s_waitcnt vmcnt(7)
	global_store_dwordx4 v22, v[76:79], s[86:87] offset:3072 nt
	s_waitcnt vmcnt(7)
	global_store_dwordx4 v23, v[80:83], s[86:87] nt
	s_waitcnt vmcnt(7)
	global_store_dwordx4 v23, v[84:87], s[86:87] offset:1024 nt
	s_waitcnt vmcnt(7)
	global_store_dwordx4 v23, v[88:91], s[86:87] offset:2048 nt
	s_waitcnt vmcnt(7)
	global_store_dwordx4 v23, v[92:95], s[86:87] offset:3072 nt

.Lmg1_end:
	v_lshrrev_b32_e32 v21, 6, v174
	v_and_b32_e32 v22, 63, v174
	v_lshlrev_b32_e32 v22, 4, v22
	v_readfirstlane_b32 s80, v21
	v_add_u32_e32 v23, 0x1000, v22
	v_readfirstlane_b32 s92, v235
	v_readfirstlane_b32 s93, v236
	v_readfirstlane_b32 s94, v237
	v_readfirstlane_b32 s95, v238
	v_readfirstlane_b32 s98, v239
	v_readfirstlane_b32 s99, v240
	s_lshr_b32 s100, s33, 7
	s_lshl_b32 s100, s100, 3
	s_lshr_b32 s101, s33, 3
	s_and_b32 s101, s101, 7
	s_add_i32 s100, s100, s101
	s_lshl_b32 s100, s100, 3
	s_add_i32 s80, s80, s100
	s_add_i32 s80, s80, 0x2474
	s_movk_i32 s100, 0x400
.Lcpy1_loop:
	s_add_i32 s101, s80, s100
	s_cmp_lt_u32 s101, 0x2630
	s_cbranch_scc0 .Lcpy1_tail
	s_mul_hi_u32 s81, s80, 0x2ad5802b
	s_lshr_b32 s81, s81, 8
	s_mul_i32 s82, s81, 0x5fa
	s_sub_i32 s82, s80, s82
	s_lshl_b32 s82, s82, 13
	s_and_b32 s83, s81, 31
	s_mul_i32 s83, s83, 0xc00000
	s_add_i32 s82, s82, s83
	s_cmp_lt_u32 s81, 32
	s_cselect_b32 s84, s92, s94
	s_cselect_b32 s85, s93, s95
	s_mov_b32 s83, 0x1f210000
	s_cselect_b32 s83, 0x7210000, s83
	s_add_u32 s84, s84, s82
	s_addc_u32 s85, s85, 0
	s_add_u32 s84, s84, 0xc000
	s_addc_u32 s85, s85, 0
	s_add_u32 s83, s83, s82
	s_add_u32 s86, s98, s83
	s_addc_u32 s87, s99, 0
	s_mul_hi_u32 s81, s101, 0x2ad5802b
	s_lshr_b32 s81, s81, 8
	s_mul_i32 s82, s81, 0x5fa
	s_sub_i32 s82, s101, s82
	s_lshl_b32 s82, s82, 13
	s_and_b32 s83, s81, 31
	s_mul_i32 s83, s83, 0xc00000
	s_add_i32 s82, s82, s83
	s_cmp_lt_u32 s81, 32
	s_cselect_b32 s88, s92, s94
	s_cselect_b32 s89, s93, s95
	s_mov_b32 s83, 0x1f210000
	s_cselect_b32 s83, 0x7210000, s83
	s_add_u32 s88, s88, s82
	s_addc_u32 s89, s89, 0
	s_add_u32 s88, s88, 0xc000
	s_addc_u32 s89, s89, 0
	s_add_u32 s83, s83, s82
	s_add_u32 s90, s98, s83
	s_addc_u32 s91, s99, 0
	global_load_dwordx4 v[64:67], v22, s[84:85] nt
	global_load_dwordx4 v[68:71], v22, s[84:85] offset:1024 nt
	global_load_dwordx4 v[72:75], v22, s[84:85] offset:2048 nt
	global_load_dwordx4 v[76:79], v22, s[84:85] offset:3072 nt
	global_load_dwordx4 v[80:83], v23, s[84:85] nt
	global_load_dwordx4 v[84:87], v23, s[84:85] offset:1024 nt
	global_load_dwordx4 v[88:91], v23, s[84:85] offset:2048 nt
	global_load_dwordx4 v[92:95], v23, s[84:85] offset:3072 nt
	global_load_dwordx4 v[96:99], v22, s[88:89] nt
	global_load_dwordx4 v[100:103], v22, s[88:89] offset:1024 nt
	global_load_dwordx4 v[104:107], v22, s[88:89] offset:2048 nt
	global_load_dwordx4 v[108:111], v22, s[88:89] offset:3072 nt
	global_load_dwordx4 v[112:115], v23, s[88:89] nt
	global_load_dwordx4 v[116:119], v23, s[88:89] offset:1024 nt
	global_load_dwordx4 v[120:123], v23, s[88:89] offset:2048 nt
	global_load_dwordx4 v[124:127], v23, s[88:89] offset:3072 nt
	s_waitcnt vmcnt(15)
	global_store_dwordx4 v22, v[64:67], s[86:87] nt
	s_waitcnt vmcnt(15)
	global_store_dwordx4 v22, v[68:71], s[86:87] offset:1024 nt
	s_waitcnt vmcnt(15)
	global_store_dwordx4 v22, v[72:75], s[86:87] offset:2048 nt
	s_waitcnt vmcnt(15)
	global_store_dwordx4 v22, v[76:79], s[86:87] offset:3072 nt
	s_waitcnt vmcnt(15)
	global_store_dwordx4 v23, v[80:83], s[86:87] nt
	s_waitcnt vmcnt(15)
	global_store_dwordx4 v23, v[84:87], s[86:87] offset:1024 nt
	s_waitcnt vmcnt(15)
	global_store_dwordx4 v23, v[88:91], s[86:87] offset:2048 nt
	s_waitcnt vmcnt(15)
	global_store_dwordx4 v23, v[92:95], s[86:87] offset:3072 nt
	s_waitcnt vmcnt(15)
	global_store_dwordx4 v22, v[96:99], s[90:91] nt
	s_waitcnt vmcnt(15)
	global_store_dwordx4 v22, v[100:103], s[90:91] offset:1024 nt
	s_waitcnt vmcnt(15)
	global_store_dwordx4 v22, v[104:107], s[90:91] offset:2048 nt
	s_waitcnt vmcnt(15)
	global_store_dwordx4 v22, v[108:111], s[90:91] offset:3072 nt
	s_waitcnt vmcnt(15)
	global_store_dwordx4 v23, v[112:115], s[90:91] nt
	s_waitcnt vmcnt(15)
	global_store_dwordx4 v23, v[116:119], s[90:91] offset:1024 nt
	s_waitcnt vmcnt(15)
	global_store_dwordx4 v23, v[120:123], s[90:91] offset:2048 nt
	s_waitcnt vmcnt(15)
	global_store_dwordx4 v23, v[124:127], s[90:91] offset:3072 nt
	s_add_i32 s80, s101, s100
	s_branch .Lcpy1_loop
.Lcpy1_tail:
	s_cmp_lt_u32 s80, 0x2630
	s_cbranch_scc0 .Lcpy1_end
	s_mul_hi_u32 s81, s80, 0x2ad5802b
	s_lshr_b32 s81, s81, 8
	s_mul_i32 s82, s81, 0x5fa
	s_sub_i32 s82, s80, s82
	s_lshl_b32 s82, s82, 13
	s_and_b32 s83, s81, 31
	s_mul_i32 s83, s83, 0xc00000
	s_add_i32 s82, s82, s83
	s_cmp_lt_u32 s81, 32
	s_cselect_b32 s84, s92, s94
	s_cselect_b32 s85, s93, s95
	s_mov_b32 s83, 0x1f210000
	s_cselect_b32 s83, 0x7210000, s83
	s_add_u32 s84, s84, s82
	s_addc_u32 s85, s85, 0
	s_add_u32 s84, s84, 0xc000
	s_addc_u32 s85, s85, 0
	s_add_u32 s83, s83, s82
	s_add_u32 s86, s98, s83
	s_addc_u32 s87, s99, 0
	global_load_dwordx4 v[64:67], v22, s[84:85] nt
	global_load_dwordx4 v[68:71], v22, s[84:85] offset:1024 nt
	global_load_dwordx4 v[72:75], v22, s[84:85] offset:2048 nt
	global_load_dwordx4 v[76:79], v22, s[84:85] offset:3072 nt
	global_load_dwordx4 v[80:83], v23, s[84:85] nt
	global_load_dwordx4 v[84:87], v23, s[84:85] offset:1024 nt
	global_load_dwordx4 v[88:91], v23, s[84:85] offset:2048 nt
	global_load_dwordx4 v[92:95], v23, s[84:85] offset:3072 nt
	s_waitcnt vmcnt(7)
	global_store_dwordx4 v22, v[64:67], s[86:87] nt
	s_waitcnt vmcnt(7)
	global_store_dwordx4 v22, v[68:71], s[86:87] offset:1024 nt
	s_waitcnt vmcnt(7)
	global_store_dwordx4 v22, v[72:75], s[86:87] offset:2048 nt
	s_waitcnt vmcnt(7)
	global_store_dwordx4 v22, v[76:79], s[86:87] offset:3072 nt
	s_waitcnt vmcnt(7)
	global_store_dwordx4 v23, v[80:83], s[86:87] nt
	s_waitcnt vmcnt(7)
	global_store_dwordx4 v23, v[84:87], s[86:87] offset:1024 nt
	s_waitcnt vmcnt(7)
	global_store_dwordx4 v23, v[88:91], s[86:87] offset:2048 nt
	s_waitcnt vmcnt(7)
	global_store_dwordx4 v23, v[92:95], s[86:87] offset:3072 nt

.LBB0_320:
	s_or_b64 exec, exec, s[6:7]
	s_add_u32 s12, s74, 0x10ae0000
	s_addc_u32 s13, s75, 0
	v_mov_b32_e32 v69, v174
	s_cmpk_gt_i32 s2, 0x8ff
	s_barrier
	s_cbranch_scc1 .LBB0_364
	v_and_b32_e32 v196, 63, v174
	v_lshrrev_b32_e32 v197, 6, v174
	v_and_b32_e32 v198, 31, v196
	v_lshrrev_b32_e32 v199, 5, v196
	s_and_b32 s80, s2, 7
	v_lshl_add_u32 v200, s80, 3, v197
	v_lshl_add_u32 v201, v200, 6, v198
	v_lshlrev_b32_e32 v202, 6, v201
	v_lshl_add_u32 v202, v199, 5, v202
	global_load_dwordx4 v[24:27], v202, s[24:25] offset:0
	global_load_dwordx4 v[28:31], v202, s[24:25] offset:16
	global_load_dwordx4 v[40:43], v202, s[24:25] offset:2048
	global_load_dwordx4 v[44:47], v202, s[24:25] offset:2064
	global_load_dwordx4 v[32:35], v202, s[26:27] offset:0
	global_load_dwordx4 v[36:39], v202, s[26:27] offset:16
	global_load_dwordx4 v[48:51], v202, s[26:27] offset:2048
	global_load_dwordx4 v[52:55], v202, s[26:27] offset:2064
	v_lshlrev_b32_e32 v203, 3, v201
	s_lshl_b32 s81, s80, 7
	v_lshl_add_u32 v204, v197, 4, s81
	v_lshl_add_u32 v204, v199, 3, v204
	v_lshlrev_b32_e32 v204, 2, v204
	global_load_dwordx4 v[140:143], v204, s[42:43]
	global_load_dwordx4 v[144:147], v204, s[42:43] offset:16
	v_lshl_add_u32 v205, v198, 12, v204
	v_lshlrev_b32_e32 v206, 2, v198
	v_lshl_add_u32 v207, v200, 6, v196
	v_lshlrev_b32_e32 v207, 3, v207
	v_mov_b32_e32 v254, 0x358637bd
	s_mov_b32 s8, 0
	s_mov_b32 s9, -1
	global_load_dwordx2 v[56:57], v203, s[10:11]
	global_load_dwordx2 v[58:59], v203, s[10:11] offset:256
	s_add_u32 s30, s74, 0x12cddc00
	s_addc_u32 s31, s75, 0
	global_load_dwordx2 v[18:19], v207, s[30:31]
	v_and_b32_e32 v172, 15, v196
	v_lshrrev_b32_e32 v173, 4, v196
	v_lshl_add_u32 v60, v200, 4, v172
	v_lshlrev_b32_e32 v202, 8, v60
	v_lshl_add_u32 v202, v173, 3, v202
	s_add_u32 s84, s74, 0x12d65c00
	s_addc_u32 s85, s75, 0
	global_load_dwordx2 v[64:65], v202, s[84:85] offset:0
	global_load_dwordx2 v[66:67], v202, s[84:85] offset:128
	global_load_dwordx2 v[68:69], v202, s[84:85] offset:32
	global_load_dwordx2 v[70:71], v202, s[84:85] offset:160
	global_load_dwordx2 v[72:73], v202, s[84:85] offset:64
	global_load_dwordx2 v[74:75], v202, s[84:85] offset:192
	global_load_dwordx2 v[76:77], v202, s[84:85] offset:96
	global_load_dwordx2 v[78:79], v202, s[84:85] offset:224
	v_lshlrev_b32_e32 v203, 2, v60
	global_load_dword v224, v203, s[58:59]
	v_mov_b32_e32 v177, 0x05040100
	v_mov_b32_e32 v244, 0x07060302
	v_min_u32_e32 v60, 7, v198
	v_lshl_add_u32 v225, v60, 12, v204
	v_lshlrev_b32_e32 v226, 2, v60
	v_mul_u32_u24_e32 v60, 0x2c00, v197
	v_mul_u32_u24_e32 v229, 0x440, v199
	v_lshl_add_u32 v229, v198, 2, v229
	v_add_u32_e32 v229, v229, v60
	v_mul_u32_u24_e32 v230, 0x110, v172
	v_lshl_add_u32 v230, v173, 4, v230
	v_add_u32_e32 v230, v230, v60
	v_lshlrev_b32_e32 v231, 6, v198
	v_lshl_add_u32 v231, v199, 5, v231
	v_add_u32_e32 v245, 0x2200, v60
	v_add_u32_e32 v231, v231, v245
	v_lshlrev_b32_e32 v232, 8, v173
	v_lshl_add_u32 v232, v172, 2, v232
	v_add_u32_e32 v232, v232, v245
	v_lshl_add_u32 v60, v200, 4, v172
	v_lshlrev_b32_e32 v60, 1, v60
	v_lshl_add_u32 v233, v173, 13, v60
	v_add_u32_e32 v241, 0x800, v233
	v_add_u32_e32 v242, 0x1000, v233
	v_add_u32_e32 v243, 0x1800, v233
	s_waitcnt vmcnt(0)
	v_mov_b32_e32 v0, v56
	v_mov_b32_e32 v4, v57
	v_mov_b32_e32 v8, v58
	v_mov_b32_e32 v14, v59
	v_mul_f32_e32 v168, v4, v4
	v_mul_f32_e32 v169, v4, v0
	v_fma_f32 v1, v0, v0, -v168
	v_fma_f32 v5, v0, v4, v169
	v_mul_f32_e32 v170, v14, v14
	v_mul_f32_e32 v171, v14, v8
	v_fma_f32 v9, v8, v8, -v170
	v_fma_f32 v15, v8, v14, v171
	v_mul_f32_e32 v168, v5, v4
	v_mul_f32_e32 v169, v5, v0
	v_fma_f32 v2, v1, v0, -v168
	v_fma_f32 v6, v1, v4, v169
	v_mul_f32_e32 v170, v15, v14
	v_mul_f32_e32 v171, v15, v8
	v_fma_f32 v10, v9, v8, -v170
	v_fma_f32 v16, v9, v14, v171
	v_mul_f32_e32 v168, v5, v5
	v_mul_f32_e32 v169, v5, v1
	v_fma_f32 v3, v1, v1, -v168
	v_fma_f32 v7, v1, v5, v169
	v_mul_f32_e32 v170, v15, v15
	v_mul_f32_e32 v171, v15, v9
	v_fma_f32 v11, v9, v9, -v170
	v_fma_f32 v17, v9, v15, v171
	v_perm_b32 v208, v66, v64, v177
	v_perm_b32 v209, v66, v64, v244
	v_perm_b32 v210, v67, v65, v177
	v_perm_b32 v211, v67, v65, v244
	v_perm_b32 v212, v70, v68, v177
	v_perm_b32 v213, v70, v68, v244
	v_perm_b32 v214, v71, v69, v177
	v_perm_b32 v215, v71, v69, v244
	v_perm_b32 v216, v74, v72, v177
	v_perm_b32 v217, v74, v72, v244
	v_perm_b32 v218, v75, v73, v177
	v_perm_b32 v219, v75, v73, v244
	v_perm_b32 v220, v78, v76, v177
	v_perm_b32 v221, v78, v76, v244
	v_perm_b32 v222, v79, v77, v177
	v_perm_b32 v223, v79, v77, v244
	v_mov_b32_e32 v22, 0
	v_mov_b32_e32 v23, 0
	s_mov_b32 s98, -1
	s_mov_b32 s99, 0
	s_mov_b32 s82, s2
	s_lshr_b32 s4, s82, 10
	s_bfe_u32 s6, s82, 0x70003
	s_lshl_b32 s4, s4, 13
	s_lshl_b32 s6, s6, 6
	s_add_i32 s31, s4, s6
	s_lshl_b32 s6, s31, 12
	s_add_u32 s84, s38, s6
	s_addc_u32 s85, s39, 0
	s_add_u32 s88, s84, 0x20000
	s_addc_u32 s89, s85, 0
	s_lshl_b32 s6, s31, 2
	s_add_u32 s86, s22, s6
	s_addc_u32 s87, s23, 0
	global_load_dwordx4 v[178:181], v205, s[84:85]
	global_load_dwordx4 v[182:185], v205, s[84:85] offset:16
	global_load_dword v194, v206, s[86:87]
	global_load_dwordx4 v[186:189], v205, s[88:89]
	global_load_dwordx4 v[190:193], v205, s[88:89] offset:16
	global_load_dword v195, v206, s[86:87] offset:128
	v_lshlrev_b32_e32 v13, 4, v196
	v_add_u32_e32 v21, 0x1000, v13
	v_readfirstlane_b32 s77, v197
	s_lshl_b32 s67, s82, 3
	s_add_i32 s67, s67, s77
	s_add_i32 s67, s67, 0xf680
	s_mul_hi_u32 s65, s67, 0x2ad5802b
	s_lshr_b32 s65, s65, 8
	s_mul_i32 s66, s65, 0x5fa
	s_sub_i32 s66, s67, s66
	s_lshl_b32 s66, s66, 13
	s_and_b32 s32, s65, 31
	s_mul_i32 s32, s32, 0xc00000
	s_add_i32 s66, s66, s32
	v_readfirstlane_b32 s84, v235
	v_readfirstlane_b32 s85, v236
	v_readfirstlane_b32 s4, v237
	v_readfirstlane_b32 s6, v238
	v_readfirstlane_b32 s100, v239
	v_readfirstlane_b32 s101, v240
	s_cmp_lt_u32 s65, 32
	s_cselect_b32 s84, s84, s4
	s_cselect_b32 s85, s85, s6
	s_mov_b32 s32, 0x1f210000
	s_cselect_b32 s32, 0x7210000, s32
	s_add_u32 s84, s84, s66
	s_addc_u32 s85, s85, 0
	s_add_u32 s84, s84, 0xc000
	s_addc_u32 s85, s85, 0
	s_add_u32 s32, s32, s66
	s_add_u32 s100, s100, s32
	s_addc_u32 s101, s101, 0
	global_load_dwordx4 v[96:99], v13, s[84:85] nt
	global_load_dwordx4 v[100:103], v13, s[84:85] offset:1024 nt
	global_load_dwordx4 v[104:107], v13, s[84:85] offset:2048 nt
	global_load_dwordx4 v[108:111], v13, s[84:85] offset:3072 nt
	global_load_dwordx4 v[112:115], v21, s[84:85] nt
	global_load_dwordx4 v[116:119], v21, s[84:85] offset:1024 nt
	global_load_dwordx4 v[120:123], v21, s[84:85] offset:2048 nt
	global_load_dwordx4 v[124:127], v21, s[84:85] offset:3072 nt

.Ls5b_cin_done:
	s_nop 1
	v_permlane32_swap_b32_e32 v128, v130
	v_permlane32_swap_b32_e32 v129, v131
	s_waitcnt vmcnt(0)
	global_store_dwordx4 v13, v[96:99], s[100:101] nt
	global_store_dwordx4 v13, v[100:103], s[100:101] offset:1024 nt
	global_store_dwordx4 v13, v[104:107], s[100:101] offset:2048 nt
	global_store_dwordx4 v13, v[108:111], s[100:101] offset:3072 nt
	global_store_dwordx4 v21, v[112:115], s[100:101] nt
	global_store_dwordx4 v21, v[116:119], s[100:101] offset:1024 nt
	global_store_dwordx4 v21, v[120:123], s[100:101] offset:2048 nt
	global_store_dwordx4 v21, v[124:127], s[100:101] offset:3072 nt
	s_add_i32 s4, s31, 0
	s_lshl_b32 s4, s4, 11
	s_add_u32 s86, s12, s4
	s_addc_u32 s87, s13, 0
	s_add_u32 s88, s86, 0x8000
	s_addc_u32 s89, s87, 0
	v_fmamk_f32 v56, v194, 0x3a800000, v254
	v_rsq_f32_e32 v56, v56
	s_nop 0
	v_pk_mul_f32 v[148:149], v[178:179], v[56:57] op_sel_hi:[1,0]
	v_pk_mul_f32 v[150:151], v[180:181], v[56:57] op_sel_hi:[1,0]
	v_pk_mul_f32 v[152:153], v[182:183], v[56:57] op_sel_hi:[1,0]
	v_pk_mul_f32 v[154:155], v[184:185], v[56:57] op_sel_hi:[1,0]
	v_pk_mul_f32 v[148:149], v[140:141], v[148:149]
	v_pk_mul_f32 v[150:151], v[142:143], v[150:151]
	v_pk_mul_f32 v[152:153], v[144:145], v[152:153]
	v_pk_mul_f32 v[154:155], v[146:147], v[154:155]
	global_load_dwordx4 v[178:181], v227, s[90:91]
	global_load_dwordx4 v[182:185], v227, s[90:91] offset:16
	global_load_dword v194, v228, s[92:93]
	ds_write_b128 v231, v[148:151] offset:0
	ds_write_b128 v231, v[152:155] offset:16
	s_nop 1
	v_mfma_f32_32x32x2_f32 v[64:79], v148, v24, 0
	v_mfma_f32_32x32x2_f32 v[80:95], v148, v32, 0
	v_mfma_f32_32x32x2_f32 v[96:111], v148, v40, 0
	v_mfma_f32_32x32x2_f32 v[112:127], v148, v48, 0
	v_mfma_f32_32x32x2_f32 v[64:79], v149, v25, v[64:79]
	v_mfma_f32_32x32x2_f32 v[80:95], v149, v33, v[80:95]
	v_mfma_f32_32x32x2_f32 v[96:111], v149, v41, v[96:111]
	v_mfma_f32_32x32x2_f32 v[112:127], v149, v49, v[112:127]
	v_mfma_f32_32x32x2_f32 v[64:79], v150, v26, v[64:79]
	v_mfma_f32_32x32x2_f32 v[80:95], v150, v34, v[80:95]
	v_mfma_f32_32x32x2_f32 v[96:111], v150, v42, v[96:111]
	v_mfma_f32_32x32x2_f32 v[112:127], v150, v50, v[112:127]
	v_mfma_f32_32x32x2_f32 v[64:79], v151, v27, v[64:79]
	v_mfma_f32_32x32x2_f32 v[80:95], v151, v35, v[80:95]
	v_mfma_f32_32x32x2_f32 v[96:111], v151, v43, v[96:111]
	v_mfma_f32_32x32x2_f32 v[112:127], v151, v51, v[112:127]
	v_mfma_f32_32x32x2_f32 v[64:79], v152, v28, v[64:79]
	v_mfma_f32_32x32x2_f32 v[80:95], v152, v36, v[80:95]
	v_mfma_f32_32x32x2_f32 v[96:111], v152, v44, v[96:111]
	v_mfma_f32_32x32x2_f32 v[112:127], v152, v52, v[112:127]
	v_mfma_f32_32x32x2_f32 v[64:79], v153, v29, v[64:79]
	v_mfma_f32_32x32x2_f32 v[80:95], v153, v37, v[80:95]
	v_mfma_f32_32x32x2_f32 v[96:111], v153, v45, v[96:111]
	v_mfma_f32_32x32x2_f32 v[112:127], v153, v53, v[112:127]
	v_mfma_f32_32x32x2_f32 v[64:79], v154, v30, v[64:79]
	v_mfma_f32_32x32x2_f32 v[80:95], v154, v38, v[80:95]
	v_mfma_f32_32x32x2_f32 v[96:111], v154, v46, v[96:111]
	v_mfma_f32_32x32x2_f32 v[112:127], v154, v54, v[112:127]
	v_mfma_f32_32x32x2_f32 v[64:79], v155, v31, v[64:79]
	v_mfma_f32_32x32x2_f32 v[80:95], v155, v39, v[80:95]
	v_mfma_f32_32x32x2_f32 v[96:111], v155, v47, v[96:111]
	v_mfma_f32_32x32x2_f32 v[112:127], v155, v55, v[112:127]
	s_nop 7
	s_nop 7
	s_nop 1
	v_fmac_f32_e32 v65, v64, v0
	v_fmac_f32_e32 v97, v96, v8
	v_fmac_f32_e32 v69, v68, v0
	v_fmac_f32_e32 v101, v100, v8
	v_fmac_f32_e32 v73, v72, v0
	v_fmac_f32_e32 v105, v104, v8
	v_fmac_f32_e32 v77, v76, v0
	v_fmac_f32_e32 v109, v108, v8
	v_fmac_f32_e32 v81, v64, v4
	v_fmac_f32_e32 v113, v96, v14
	v_fmac_f32_e32 v85, v68, v4
	v_fmac_f32_e32 v117, v100, v14
	v_fmac_f32_e32 v89, v72, v4
	v_fmac_f32_e32 v121, v104, v14
	v_fmac_f32_e32 v93, v76, v4
	v_fmac_f32_e32 v125, v108, v14
	v_fma_f32 v65, -v80, v4, v65
	v_fma_f32 v97, -v112, v14, v97
	v_fma_f32 v69, -v84, v4, v69
	v_fma_f32 v101, -v116, v14, v101
	v_fma_f32 v73, -v88, v4, v73
	v_fma_f32 v105, -v120, v14, v105
	v_fma_f32 v77, -v92, v4, v77
	v_fma_f32 v109, -v124, v14, v109
	v_fmac_f32_e32 v81, v80, v0
	v_fmac_f32_e32 v113, v112, v8
	v_fmac_f32_e32 v85, v84, v0
	v_fmac_f32_e32 v117, v116, v8
	v_fmac_f32_e32 v89, v88, v0
	v_fmac_f32_e32 v121, v120, v8
	v_fmac_f32_e32 v93, v92, v0
	v_fmac_f32_e32 v125, v124, v8
	v_fmac_f32_e32 v66, v65, v0
	v_fmac_f32_e32 v98, v97, v8
	v_fmac_f32_e32 v70, v69, v0
	v_fmac_f32_e32 v102, v101, v8
	v_fmac_f32_e32 v74, v73, v0
	v_fmac_f32_e32 v106, v105, v8
	v_fmac_f32_e32 v78, v77, v0
	v_fmac_f32_e32 v110, v109, v8
	v_fmac_f32_e32 v82, v65, v4
	v_fmac_f32_e32 v114, v97, v14
	v_fmac_f32_e32 v86, v69, v4
	v_fmac_f32_e32 v118, v101, v14
	v_fmac_f32_e32 v90, v73, v4
	v_fmac_f32_e32 v122, v105, v14
	v_fmac_f32_e32 v94, v77, v4
	v_fmac_f32_e32 v126, v109, v14
	v_fma_f32 v66, -v81, v4, v66
	v_fma_f32 v98, -v113, v14, v98
	v_fma_f32 v70, -v85, v4, v70
	v_fma_f32 v102, -v117, v14, v102
	v_fma_f32 v74, -v89, v4, v74
	v_fma_f32 v106, -v121, v14, v106
	v_fma_f32 v78, -v93, v4, v78
	v_fma_f32 v110, -v125, v14, v110
	v_fmac_f32_e32 v82, v81, v0
	v_fmac_f32_e32 v114, v113, v8
	v_fmac_f32_e32 v86, v85, v0
	v_fmac_f32_e32 v118, v117, v8
	v_fmac_f32_e32 v90, v89, v0
	v_fmac_f32_e32 v122, v121, v8
	v_fmac_f32_e32 v94, v93, v0
	v_fmac_f32_e32 v126, v125, v8
	v_fmac_f32_e32 v67, v66, v0
	v_fmac_f32_e32 v99, v98, v8
	v_fmac_f32_e32 v71, v70, v0
	v_fmac_f32_e32 v103, v102, v8
	v_fmac_f32_e32 v75, v74, v0
	v_fmac_f32_e32 v107, v106, v8
	v_fmac_f32_e32 v79, v78, v0
	v_fmac_f32_e32 v111, v110, v8
	v_fmac_f32_e32 v83, v66, v4
	v_fmac_f32_e32 v115, v98, v14
	v_fmac_f32_e32 v87, v70, v4
	v_fmac_f32_e32 v119, v102, v14
	v_fmac_f32_e32 v91, v74, v4
	v_fmac_f32_e32 v123, v106, v14
	v_fmac_f32_e32 v95, v78, v4
	v_fmac_f32_e32 v127, v110, v14
	v_fma_f32 v67, -v82, v4, v67
	v_fma_f32 v99, -v114, v14, v99
	v_fma_f32 v71, -v86, v4, v71
	v_fma_f32 v103, -v118, v14, v103
	v_fma_f32 v75, -v90, v4, v75
	v_fma_f32 v107, -v122, v14, v107
	v_fma_f32 v79, -v94, v4, v79
	v_fma_f32 v111, -v126, v14, v111
	v_fmac_f32_e32 v83, v82, v0
	v_fmac_f32_e32 v115, v114, v8
	v_fmac_f32_e32 v87, v86, v0
	v_fmac_f32_e32 v119, v118, v8
	v_fmac_f32_e32 v91, v90, v0
	v_fmac_f32_e32 v123, v122, v8
	v_fmac_f32_e32 v95, v94, v0
	v_fmac_f32_e32 v127, v126, v8
	v_mov_b32_e32 v158, v67
	v_mov_b32_e32 v160, v67
	v_mov_b32_e32 v159, v83
	v_mov_b32_e32 v161, v83
	v_mov_b32_e32 v164, v99
	v_mov_b32_e32 v166, v99
	v_mov_b32_e32 v165, v115
	v_mov_b32_e32 v167, v115
	s_nop 1
	v_permlane32_swap_b32_e32 v158, v160
	v_permlane32_swap_b32_e32 v159, v161
	v_permlane32_swap_b32_e32 v164, v166
	v_permlane32_swap_b32_e32 v165, v167
	v_fma_f32 v168, v128, v3, v158
	v_fma_f32 v170, v130, v11, v164
	v_fma_f32 v169, v128, v7, v159
	v_fma_f32 v171, v130, v17, v165
	v_fma_f32 v132, -v129, v7, v168
	v_fma_f32 v134, -v131, v17, v170
	v_fma_f32 v133, v129, v3, v169
	v_fma_f32 v135, v131, v11, v171
	v_cndmask_b32_e64 v136, v128, v132, s[8:9]
	v_cndmask_b32_e64 v137, v129, v133, s[8:9]
	v_cndmask_b32_e64 v156, v130, v134, s[8:9]
	v_cndmask_b32_e64 v157, v131, v135, s[8:9]
	v_fma_f32 v168, v132, v3, v160
	v_fma_f32 v170, v134, v11, v166
	v_fma_f32 v169, v132, v7, v161
	v_fma_f32 v171, v134, v17, v167
	v_fma_f32 v128, -v133, v7, v168
	v_fma_f32 v130, -v135, v17, v170
	v_fma_f32 v129, v133, v3, v169
	v_fma_f32 v131, v135, v11, v171
	v_mov_b32_e32 v246, v128
	v_mov_b32_e32 v247, v129
	v_mov_b32_e32 v248, v130
	v_mov_b32_e32 v249, v131
	v_pk_fma_f32 v[64:65], v[0:1], v[136:137], v[64:65] op_sel_hi:[1,0,1]
	v_mov_b32_e32 v158, v71
	v_pk_fma_f32 v[80:81], v[0:1], v[136:137], v[80:81] op_sel:[0,1,0]
	v_mov_b32_e32 v160, v71
	v_pk_fma_f32 v[66:67], v[2:3], v[136:137], v[66:67] op_sel_hi:[1,0,1]
	v_mov_b32_e32 v159, v87
	v_pk_fma_f32 v[82:83], v[2:3], v[136:137], v[82:83] op_sel:[0,1,0]
	v_mov_b32_e32 v161, v87
	v_pk_fma_f32 v[96:97], v[8:9], v[156:157], v[96:97] op_sel_hi:[1,0,1]
	v_mov_b32_e32 v164, v103
	v_pk_fma_f32 v[112:113], v[8:9], v[156:157], v[112:113] op_sel:[0,1,0]
	v_mov_b32_e32 v166, v103
	v_pk_fma_f32 v[98:99], v[10:11], v[156:157], v[98:99] op_sel_hi:[1,0,1]
	v_mov_b32_e32 v165, v119
	v_pk_fma_f32 v[114:115], v[10:11], v[156:157], v[114:115] op_sel:[0,1,0]
	v_mov_b32_e32 v167, v119
	v_pk_fma_f32 v[64:65], v[4:5], v[136:137], v[64:65] op_sel:[0,1,0] neg_lo:[1,0,0] neg_hi:[1,0,0]
	s_nop 1
	v_pk_fma_f32 v[80:81], v[4:5], v[136:137], v[80:81] op_sel_hi:[1,0,1]
	v_permlane32_swap_b32_e32 v158, v160
	v_pk_fma_f32 v[66:67], v[6:7], v[136:137], v[66:67] op_sel:[0,1,0] neg_lo:[1,0,0] neg_hi:[1,0,0]
	v_permlane32_swap_b32_e32 v159, v161
	v_pk_fma_f32 v[82:83], v[6:7], v[136:137], v[82:83] op_sel_hi:[1,0,1]
	v_permlane32_swap_b32_e32 v164, v166
	v_pk_fma_f32 v[96:97], v[14:15], v[156:157], v[96:97] op_sel:[0,1,0] neg_lo:[1,0,0] neg_hi:[1,0,0]
	v_permlane32_swap_b32_e32 v165, v167
	v_pk_fma_f32 v[112:113], v[14:15], v[156:157], v[112:113] op_sel_hi:[1,0,1]
	v_fma_f32 v168, v128, v3, v158
	v_pk_fma_f32 v[98:99], v[16:17], v[156:157], v[98:99] op_sel:[0,1,0] neg_lo:[1,0,0] neg_hi:[1,0,0]
	v_fma_f32 v170, v130, v11, v164
	v_pk_fma_f32 v[114:115], v[16:17], v[156:157], v[114:115] op_sel_hi:[1,0,1]
	v_fma_f32 v169, v128, v7, v159
	v_fma_f32 v171, v130, v17, v165
	v_fma_f32 v132, -v129, v7, v168
	v_fma_f32 v134, -v131, v17, v170
	v_fma_f32 v133, v129, v3, v169
	v_fma_f32 v135, v131, v11, v171
	v_cndmask_b32_e64 v172, v128, v132, s[8:9]
	v_cndmask_b32_e64 v173, v129, v133, s[8:9]
	v_cndmask_b32_e64 v244, v130, v134, s[8:9]
	v_cndmask_b32_e64 v245, v131, v135, s[8:9]
	v_fma_f32 v168, v132, v3, v160
	v_fma_f32 v170, v134, v11, v166
	v_fma_f32 v169, v132, v7, v161
	v_fma_f32 v171, v134, v17, v167
	v_fma_f32 v128, -v133, v7, v168
	v_fma_f32 v130, -v135, v17, v170
	v_fma_f32 v129, v133, v3, v169
	v_fma_f32 v131, v135, v11, v171
	v_pk_fma_f32 v[68:69], v[0:1], v[172:173], v[68:69] op_sel_hi:[1,0,1]
	v_mov_b32_e32 v158, v75
	v_pk_fma_f32 v[84:85], v[0:1], v[172:173], v[84:85] op_sel:[0,1,0]
	v_mov_b32_e32 v160, v75
	v_pk_fma_f32 v[70:71], v[2:3], v[172:173], v[70:71] op_sel_hi:[1,0,1]
	v_mov_b32_e32 v159, v91
	v_pk_fma_f32 v[86:87], v[2:3], v[172:173], v[86:87] op_sel:[0,1,0]
	v_mov_b32_e32 v161, v91
	v_pk_fma_f32 v[100:101], v[8:9], v[244:245], v[100:101] op_sel_hi:[1,0,1]
	v_mov_b32_e32 v164, v107
	v_pk_fma_f32 v[116:117], v[8:9], v[244:245], v[116:117] op_sel:[0,1,0]
	v_mov_b32_e32 v166, v107
	v_pk_fma_f32 v[102:103], v[10:11], v[244:245], v[102:103] op_sel_hi:[1,0,1]
	v_mov_b32_e32 v165, v123
	v_pk_fma_f32 v[118:119], v[10:11], v[244:245], v[118:119] op_sel:[0,1,0]
	v_mov_b32_e32 v167, v123
	v_pk_fma_f32 v[68:69], v[4:5], v[172:173], v[68:69] op_sel:[0,1,0] neg_lo:[1,0,0] neg_hi:[1,0,0]
	s_nop 1
	v_pk_fma_f32 v[84:85], v[4:5], v[172:173], v[84:85] op_sel_hi:[1,0,1]
	v_permlane32_swap_b32_e32 v158, v160
	v_pk_fma_f32 v[70:71], v[6:7], v[172:173], v[70:71] op_sel:[0,1,0] neg_lo:[1,0,0] neg_hi:[1,0,0]
	v_permlane32_swap_b32_e32 v159, v161
	v_pk_fma_f32 v[86:87], v[6:7], v[172:173], v[86:87] op_sel_hi:[1,0,1]
	v_permlane32_swap_b32_e32 v164, v166
	v_pk_fma_f32 v[100:101], v[14:15], v[244:245], v[100:101] op_sel:[0,1,0] neg_lo:[1,0,0] neg_hi:[1,0,0]
	v_permlane32_swap_b32_e32 v165, v167
	v_pk_fma_f32 v[116:117], v[14:15], v[244:245], v[116:117] op_sel_hi:[1,0,1]
	v_fma_f32 v168, v128, v3, v158
	v_pk_fma_f32 v[102:103], v[16:17], v[244:245], v[102:103] op_sel:[0,1,0] neg_lo:[1,0,0] neg_hi:[1,0,0]
	v_fma_f32 v170, v130, v11, v164
	v_pk_fma_f32 v[118:119], v[16:17], v[244:245], v[118:119] op_sel_hi:[1,0,1]
	v_fma_f32 v169, v128, v7, v159
	v_fma_f32 v171, v130, v17, v165
	v_fma_f32 v132, -v129, v7, v168
	v_fma_f32 v134, -v131, v17, v170
	v_fma_f32 v133, v129, v3, v169
	v_fma_f32 v135, v131, v11, v171
	v_cndmask_b32_e64 v136, v128, v132, s[8:9]
	v_cndmask_b32_e64 v137, v129, v133, s[8:9]
	v_cndmask_b32_e64 v156, v130, v134, s[8:9]
	v_cndmask_b32_e64 v157, v131, v135, s[8:9]
	v_fma_f32 v168, v132, v3, v160
	v_fma_f32 v170, v134, v11, v166
	v_fma_f32 v169, v132, v7, v161
	v_fma_f32 v171, v134, v17, v167
	v_fma_f32 v128, -v133, v7, v168
	v_fma_f32 v130, -v135, v17, v170
	v_fma_f32 v129, v133, v3, v169
	v_fma_f32 v131, v135, v11, v171
	v_pk_fma_f32 v[72:73], v[0:1], v[136:137], v[72:73] op_sel_hi:[1,0,1]
	v_mov_b32_e32 v158, v79
	v_pk_fma_f32 v[88:89], v[0:1], v[136:137], v[88:89] op_sel:[0,1,0]
	v_mov_b32_e32 v160, v79
	v_pk_fma_f32 v[74:75], v[2:3], v[136:137], v[74:75] op_sel_hi:[1,0,1]
	v_mov_b32_e32 v159, v95
	v_pk_fma_f32 v[90:91], v[2:3], v[136:137], v[90:91] op_sel:[0,1,0]
	v_mov_b32_e32 v161, v95
	v_pk_fma_f32 v[104:105], v[8:9], v[156:157], v[104:105] op_sel_hi:[1,0,1]
	v_mov_b32_e32 v164, v111
	v_pk_fma_f32 v[120:121], v[8:9], v[156:157], v[120:121] op_sel:[0,1,0]
	v_mov_b32_e32 v166, v111
	v_pk_fma_f32 v[106:107], v[10:11], v[156:157], v[106:107] op_sel_hi:[1,0,1]
	v_mov_b32_e32 v165, v127
	v_pk_fma_f32 v[122:123], v[10:11], v[156:157], v[122:123] op_sel:[0,1,0]
	v_mov_b32_e32 v167, v127
	v_pk_fma_f32 v[72:73], v[4:5], v[136:137], v[72:73] op_sel:[0,1,0] neg_lo:[1,0,0] neg_hi:[1,0,0]
	s_nop 1
	v_pk_fma_f32 v[88:89], v[4:5], v[136:137], v[88:89] op_sel_hi:[1,0,1]
	v_permlane32_swap_b32_e32 v158, v160
	v_pk_fma_f32 v[74:75], v[6:7], v[136:137], v[74:75] op_sel:[0,1,0] neg_lo:[1,0,0] neg_hi:[1,0,0]
	v_permlane32_swap_b32_e32 v159, v161
	v_pk_fma_f32 v[90:91], v[6:7], v[136:137], v[90:91] op_sel_hi:[1,0,1]
	v_permlane32_swap_b32_e32 v164, v166
	v_pk_fma_f32 v[104:105], v[14:15], v[156:157], v[104:105] op_sel:[0,1,0] neg_lo:[1,0,0] neg_hi:[1,0,0]
	v_permlane32_swap_b32_e32 v165, v167
	v_pk_fma_f32 v[120:121], v[14:15], v[156:157], v[120:121] op_sel_hi:[1,0,1]
	v_fma_f32 v168, v128, v3, v158
	v_pk_fma_f32 v[106:107], v[16:17], v[156:157], v[106:107] op_sel:[0,1,0] neg_lo:[1,0,0] neg_hi:[1,0,0]
	v_fma_f32 v170, v130, v11, v164
	v_pk_fma_f32 v[122:123], v[16:17], v[156:157], v[122:123] op_sel_hi:[1,0,1]
	v_fma_f32 v169, v128, v7, v159
	v_fma_f32 v171, v130, v17, v165
	v_fma_f32 v132, -v129, v7, v168
	v_fma_f32 v134, -v131, v17, v170
	v_fma_f32 v133, v129, v3, v169
	v_fma_f32 v135, v131, v11, v171
	v_cndmask_b32_e64 v172, v128, v132, s[8:9]
	v_cndmask_b32_e64 v173, v129, v133, s[8:9]
	v_cndmask_b32_e64 v244, v130, v134, s[8:9]
	v_cndmask_b32_e64 v245, v131, v135, s[8:9]
	v_fma_f32 v168, v132, v3, v160
	v_fma_f32 v170, v134, v11, v166
	v_fma_f32 v169, v132, v7, v161
	v_fma_f32 v171, v134, v17, v167
	v_fma_f32 v128, -v133, v7, v168
	v_fma_f32 v130, -v135, v17, v170
	v_fma_f32 v129, v133, v3, v169
	v_fma_f32 v131, v135, v11, v171
	v_pk_fma_f32 v[76:77], v[0:1], v[172:173], v[76:77] op_sel_hi:[1,0,1]
	v_pk_fma_f32 v[92:93], v[0:1], v[172:173], v[92:93] op_sel:[0,1,0]
	v_pk_fma_f32 v[78:79], v[2:3], v[172:173], v[78:79] op_sel_hi:[1,0,1]
	v_pk_fma_f32 v[94:95], v[2:3], v[172:173], v[94:95] op_sel:[0,1,0]
	v_pk_fma_f32 v[108:109], v[8:9], v[244:245], v[108:109] op_sel_hi:[1,0,1]
	v_pk_fma_f32 v[124:125], v[8:9], v[244:245], v[124:125] op_sel:[0,1,0]
	v_pk_fma_f32 v[110:111], v[10:11], v[244:245], v[110:111] op_sel_hi:[1,0,1]
	v_pk_fma_f32 v[126:127], v[10:11], v[244:245], v[126:127] op_sel:[0,1,0]
	v_pk_fma_f32 v[76:77], v[4:5], v[172:173], v[76:77] op_sel:[0,1,0] neg_lo:[1,0,0] neg_hi:[1,0,0]
	v_pk_fma_f32 v[92:93], v[4:5], v[172:173], v[92:93] op_sel_hi:[1,0,1]
	v_pk_fma_f32 v[78:79], v[6:7], v[172:173], v[78:79] op_sel:[0,1,0] neg_lo:[1,0,0] neg_hi:[1,0,0]
	v_pk_fma_f32 v[94:95], v[6:7], v[172:173], v[94:95] op_sel_hi:[1,0,1]
	v_pk_fma_f32 v[108:109], v[14:15], v[244:245], v[108:109] op_sel:[0,1,0] neg_lo:[1,0,0] neg_hi:[1,0,0]
	v_pk_fma_f32 v[124:125], v[14:15], v[244:245], v[124:125] op_sel_hi:[1,0,1]
	v_pk_fma_f32 v[110:111], v[16:17], v[244:245], v[110:111] op_sel:[0,1,0] neg_lo:[1,0,0] neg_hi:[1,0,0]
	v_pk_fma_f32 v[126:127], v[16:17], v[244:245], v[126:127] op_sel_hi:[1,0,1]
	v_cvt_pk_bf16_f32 v56, v64, v80
	ds_write_b32 v229, v56 offset:0
	v_cvt_pk_bf16_f32 v57, v96, v112
	ds_write_b32 v229, v57 offset:128
	v_cvt_pk_bf16_f32 v58, v65, v81
	ds_write_b32 v229, v58 offset:272
	v_cvt_pk_bf16_f32 v59, v97, v113
	ds_write_b32 v229, v59 offset:400
	v_cvt_pk_bf16_f32 v56, v66, v82
	ds_write_b32 v229, v56 offset:544
	v_cvt_pk_bf16_f32 v57, v98, v114
	ds_write_b32 v229, v57 offset:672
	v_cvt_pk_bf16_f32 v58, v67, v83
	ds_write_b32 v229, v58 offset:816
	v_cvt_pk_bf16_f32 v59, v99, v115
	ds_write_b32 v229, v59 offset:944
	v_cvt_pk_bf16_f32 v56, v68, v84
	ds_write_b32 v229, v56 offset:2176
	v_cvt_pk_bf16_f32 v57, v100, v116
	ds_write_b32 v229, v57 offset:2304
	v_cvt_pk_bf16_f32 v58, v69, v85
	ds_write_b32 v229, v58 offset:2448
	v_cvt_pk_bf16_f32 v59, v101, v117
	ds_write_b32 v229, v59 offset:2576
	v_cvt_pk_bf16_f32 v56, v70, v86
	ds_write_b32 v229, v56 offset:2720
	v_cvt_pk_bf16_f32 v57, v102, v118
	ds_write_b32 v229, v57 offset:2848
	v_cvt_pk_bf16_f32 v58, v71, v87
	ds_write_b32 v229, v58 offset:2992
	v_cvt_pk_bf16_f32 v59, v103, v119
	ds_write_b32 v229, v59 offset:3120
	v_cvt_pk_bf16_f32 v56, v72, v88
	ds_write_b32 v229, v56 offset:4352
	v_cvt_pk_bf16_f32 v57, v104, v120
	ds_write_b32 v229, v57 offset:4480
	v_cvt_pk_bf16_f32 v58, v73, v89
	ds_write_b32 v229, v58 offset:4624
	v_cvt_pk_bf16_f32 v59, v105, v121
	ds_write_b32 v229, v59 offset:4752
	v_cvt_pk_bf16_f32 v56, v74, v90
	ds_write_b32 v229, v56 offset:4896
	v_cvt_pk_bf16_f32 v57, v106, v122
	ds_write_b32 v229, v57 offset:5024
	v_cvt_pk_bf16_f32 v58, v75, v91
	ds_write_b32 v229, v58 offset:5168
	v_cvt_pk_bf16_f32 v59, v107, v123
	ds_write_b32 v229, v59 offset:5296
	v_cvt_pk_bf16_f32 v56, v76, v92
	ds_write_b32 v229, v56 offset:6528
	v_cvt_pk_bf16_f32 v57, v108, v124
	ds_write_b32 v229, v57 offset:6656
	v_cvt_pk_bf16_f32 v58, v77, v93
	ds_write_b32 v229, v58 offset:6800
	v_cvt_pk_bf16_f32 v59, v109, v125
	ds_write_b32 v229, v59 offset:6928
	v_cvt_pk_bf16_f32 v56, v78, v94
	ds_write_b32 v229, v56 offset:7072
	v_cvt_pk_bf16_f32 v57, v110, v126
	ds_write_b32 v229, v57 offset:7200
	v_cvt_pk_bf16_f32 v58, v79, v95
	ds_write_b32 v229, v58 offset:7344
	v_cvt_pk_bf16_f32 v59, v111, v127
	ds_write_b32 v229, v59 offset:7472
	ds_read_b128 v[164:167], v230 offset:0
	ds_read_b128 v[168:171], v230 offset:64
	ds_read_b128 v[156:159], v230 offset:128
	ds_read_b128 v[132:135], v230 offset:192
	ds_read_b32 v56, v232 offset:0
	ds_read_b32 v57, v232 offset:64
	ds_read_b32 v58, v232 offset:128
	ds_read_b32 v59, v232 offset:192
	s_waitcnt lgkmcnt(7)
	v_mfma_f32_16x16x32_bf16 v[250:253], v[164:167], v[208:211], 0
	s_waitcnt lgkmcnt(6)
	v_mfma_f32_16x16x32_bf16 v[250:253], v[168:171], v[212:215], v[250:253]
	s_waitcnt lgkmcnt(5)
	v_mfma_f32_16x16x32_bf16 v[250:253], v[156:159], v[216:219], v[250:253]
	s_waitcnt lgkmcnt(4)
	v_mfma_f32_16x16x32_bf16 v[250:253], v[132:135], v[220:223], v[250:253]
	s_waitcnt lgkmcnt(0)
	s_nop 7
	s_nop 1
	v_fma_f32 v250, v224, v56, v250
	v_fma_f32 v251, v224, v57, v251
	v_fma_f32 v252, v224, v58, v252
	v_fma_f32 v253, v224, v59, v253
	v_mul_f32_e32 v60, 0x3d372713, v250
	v_mul_f32_e32 v172, 0x3d372713, v251
	v_mul_f32_e32 v173, 0x3d372713, v252
	v_mul_f32_e32 v245, 0x3d372713, v253
	v_mul_f32_e32 v60, v250, v60
	v_mul_f32_e32 v172, v251, v172
	v_mul_f32_e32 v173, v252, v173
	v_mul_f32_e32 v245, v253, v245
	v_fma_f32 v60, v250, v60, v250
	v_fma_f32 v172, v251, v172, v251
	v_fma_f32 v173, v252, v173, v252
	v_fma_f32 v245, v253, v245, v253
	v_mul_f32_e32 v60, 0x3f4c422a, v60
	v_mul_f32_e32 v172, 0x3f4c422a, v172
	v_mul_f32_e32 v173, 0x3f4c422a, v173
	v_mul_f32_e32 v245, 0x3f4c422a, v245
	v_add_f32_e32 v60, v60, v60
	v_add_f32_e32 v172, v172, v172
	v_add_f32_e32 v173, v173, v173
	v_add_f32_e32 v245, v245, v245
	v_mul_f32_e32 v60, 0x3fb8aa3b, v60
	v_mul_f32_e32 v172, 0x3fb8aa3b, v172
	v_mul_f32_e32 v173, 0x3fb8aa3b, v173
	v_mul_f32_e32 v245, 0x3fb8aa3b, v245
	v_exp_f32_e32 v60, v60
	v_exp_f32_e32 v172, v172
	v_exp_f32_e32 v173, v173
	v_exp_f32_e32 v245, v245
	v_mul_f32_e32 v250, 0.5, v250
	v_mul_f32_e32 v251, 0.5, v251
	v_mul_f32_e32 v252, 0.5, v252
	v_mul_f32_e32 v253, 0.5, v253
	v_add_f32_e32 v60, 1.0, v60
	v_add_f32_e32 v172, 1.0, v172
	v_add_f32_e32 v173, 1.0, v173
	v_add_f32_e32 v245, 1.0, v245
	v_rcp_f32_e32 v60, v60
	v_rcp_f32_e32 v172, v172
	v_rcp_f32_e32 v173, v173
	v_rcp_f32_e32 v245, v245
	s_nop 0
	v_fma_f32 v60, v60, -2.0, 1.0
	v_fma_f32 v172, v172, -2.0, 1.0
	v_fma_f32 v173, v173, -2.0, 1.0
	v_fma_f32 v245, v245, -2.0, 1.0
	v_add_f32_e32 v60, 1.0, v60
	v_add_f32_e32 v172, 1.0, v172
	v_add_f32_e32 v173, 1.0, v173
	v_add_f32_e32 v245, 1.0, v245
	v_mul_f32_e32 v250, v250, v60
	v_mul_f32_e32 v251, v251, v172
	v_mul_f32_e32 v252, v252, v173
	v_mul_f32_e32 v253, v253, v245
	v_cvt_pk_bf16_f32 v250, v250, 0
	v_cvt_pk_bf16_f32 v251, v251, 0
	v_cvt_pk_bf16_f32 v252, v252, 0
	v_cvt_pk_bf16_f32 v253, v253, 0
	s_cmp_lg_u32 s35, 0
	s_cselect_b32 s4, 0, -1
	s_mov_b32 exec_hi, s4
	global_store_short v233, v250, s[86:87]
	global_store_short v241, v251, s[86:87]
	global_store_short v242, v252, s[86:87]
	global_store_short v243, v253, s[86:87]
	s_mov_b32 exec_hi, -1
	s_cmp_lg_u32 s35, 0
	s_cbranch_scc1 .Ls5b_ep_skip0
	ds_read_b128 v[164:167], v230 offset:4352
	ds_read_b128 v[168:171], v230 offset:4416
	ds_read_b128 v[156:159], v230 offset:4480
	ds_read_b128 v[132:135], v230 offset:4544
	ds_read_b32 v56, v232 offset:1024
	ds_read_b32 v57, v232 offset:1088
	ds_read_b32 v58, v232 offset:1152
	ds_read_b32 v59, v232 offset:1216
	s_waitcnt lgkmcnt(7)
	v_mfma_f32_16x16x32_bf16 v[250:253], v[164:167], v[208:211], 0
	s_waitcnt lgkmcnt(6)
	v_mfma_f32_16x16x32_bf16 v[250:253], v[168:171], v[212:215], v[250:253]
	s_waitcnt lgkmcnt(5)
	v_mfma_f32_16x16x32_bf16 v[250:253], v[156:159], v[216:219], v[250:253]
	s_waitcnt lgkmcnt(4)
	v_mfma_f32_16x16x32_bf16 v[250:253], v[132:135], v[220:223], v[250:253]
	s_waitcnt lgkmcnt(0)
	s_nop 7
	s_nop 1
	v_fma_f32 v250, v224, v56, v250
	v_fma_f32 v251, v224, v57, v251
	v_fma_f32 v252, v224, v58, v252
	v_fma_f32 v253, v224, v59, v253
	v_mul_f32_e32 v60, 0x3d372713, v250
	v_mul_f32_e32 v172, 0x3d372713, v251
	v_mul_f32_e32 v173, 0x3d372713, v252
	v_mul_f32_e32 v245, 0x3d372713, v253
	v_mul_f32_e32 v60, v250, v60
	v_mul_f32_e32 v172, v251, v172
	v_mul_f32_e32 v173, v252, v173
	v_mul_f32_e32 v245, v253, v245
	v_fma_f32 v60, v250, v60, v250
	v_fma_f32 v172, v251, v172, v251
	v_fma_f32 v173, v252, v173, v252
	v_fma_f32 v245, v253, v245, v253
	v_mul_f32_e32 v60, 0x3f4c422a, v60
	v_mul_f32_e32 v172, 0x3f4c422a, v172
	v_mul_f32_e32 v173, 0x3f4c422a, v173
	v_mul_f32_e32 v245, 0x3f4c422a, v245
	v_add_f32_e32 v60, v60, v60
	v_add_f32_e32 v172, v172, v172
	v_add_f32_e32 v173, v173, v173
	v_add_f32_e32 v245, v245, v245
	v_mul_f32_e32 v60, 0x3fb8aa3b, v60
	v_mul_f32_e32 v172, 0x3fb8aa3b, v172
	v_mul_f32_e32 v173, 0x3fb8aa3b, v173
	v_mul_f32_e32 v245, 0x3fb8aa3b, v245
	v_exp_f32_e32 v60, v60
	v_exp_f32_e32 v172, v172
	v_exp_f32_e32 v173, v173
	v_exp_f32_e32 v245, v245
	v_mul_f32_e32 v250, 0.5, v250
	v_mul_f32_e32 v251, 0.5, v251
	v_mul_f32_e32 v252, 0.5, v252
	v_mul_f32_e32 v253, 0.5, v253
	v_add_f32_e32 v60, 1.0, v60
	v_add_f32_e32 v172, 1.0, v172
	v_add_f32_e32 v173, 1.0, v173
	v_add_f32_e32 v245, 1.0, v245
	v_rcp_f32_e32 v60, v60
	v_rcp_f32_e32 v172, v172
	v_rcp_f32_e32 v173, v173
	v_rcp_f32_e32 v245, v245
	s_nop 0
	v_fma_f32 v60, v60, -2.0, 1.0
	v_fma_f32 v172, v172, -2.0, 1.0
	v_fma_f32 v173, v173, -2.0, 1.0
	v_fma_f32 v245, v245, -2.0, 1.0
	v_add_f32_e32 v60, 1.0, v60
	v_add_f32_e32 v172, 1.0, v172
	v_add_f32_e32 v173, 1.0, v173
	v_add_f32_e32 v245, 1.0, v245
	v_mul_f32_e32 v250, v250, v60
	v_mul_f32_e32 v251, v251, v172
	v_mul_f32_e32 v252, v252, v173
	v_mul_f32_e32 v253, v253, v245
	v_cvt_pk_bf16_f32 v250, v250, 0
	v_cvt_pk_bf16_f32 v251, v251, 0
	v_cvt_pk_bf16_f32 v252, v252, 0
	v_cvt_pk_bf16_f32 v253, v253, 0
	global_store_short v233, v250, s[88:89]
	global_store_short v241, v251, s[88:89]
	global_store_short v242, v252, s[88:89]
	global_store_short v243, v253, s[88:89]
.Ls5b_ep_skip0:
	s_cmp_lg_u32 s35, 0
	s_cbranch_scc1 .Ls5b_item_end
	s_add_i32 s4, s31, 32
	s_lshl_b32 s4, s4, 11
	s_add_u32 s86, s12, s4
	s_addc_u32 s87, s13, 0
	s_add_u32 s88, s86, 0x8000
	s_addc_u32 s89, s87, 0
	v_fmamk_f32 v56, v195, 0x3a800000, v254
	v_rsq_f32_e32 v56, v56
	s_nop 0
	v_pk_mul_f32 v[148:149], v[186:187], v[56:57] op_sel_hi:[1,0]
	v_pk_mul_f32 v[150:151], v[188:189], v[56:57] op_sel_hi:[1,0]
	v_pk_mul_f32 v[152:153], v[190:191], v[56:57] op_sel_hi:[1,0]
	v_pk_mul_f32 v[154:155], v[192:193], v[56:57] op_sel_hi:[1,0]
	v_pk_mul_f32 v[148:149], v[140:141], v[148:149]
	v_pk_mul_f32 v[150:151], v[142:143], v[150:151]
	v_pk_mul_f32 v[152:153], v[144:145], v[152:153]
	v_pk_mul_f32 v[154:155], v[146:147], v[154:155]
	global_load_dwordx4 v[186:189], v227, s[94:95]
	global_load_dwordx4 v[190:193], v227, s[94:95] offset:16
	global_load_dword v195, v228, s[92:93] offset:128
	ds_write_b128 v231, v[148:151] offset:0
	ds_write_b128 v231, v[152:155] offset:16
	s_nop 1
	v_mfma_f32_32x32x2_f32 v[64:79], v148, v24, 0
	v_mfma_f32_32x32x2_f32 v[80:95], v148, v32, 0
	v_mfma_f32_32x32x2_f32 v[96:111], v148, v40, 0
	v_mfma_f32_32x32x2_f32 v[112:127], v148, v48, 0
	v_mfma_f32_32x32x2_f32 v[64:79], v149, v25, v[64:79]
	v_mfma_f32_32x32x2_f32 v[80:95], v149, v33, v[80:95]
	v_mfma_f32_32x32x2_f32 v[96:111], v149, v41, v[96:111]
	v_mfma_f32_32x32x2_f32 v[112:127], v149, v49, v[112:127]
	v_mfma_f32_32x32x2_f32 v[64:79], v150, v26, v[64:79]
	v_mfma_f32_32x32x2_f32 v[80:95], v150, v34, v[80:95]
	v_mfma_f32_32x32x2_f32 v[96:111], v150, v42, v[96:111]
	v_mfma_f32_32x32x2_f32 v[112:127], v150, v50, v[112:127]
	v_mfma_f32_32x32x2_f32 v[64:79], v151, v27, v[64:79]
	v_mfma_f32_32x32x2_f32 v[80:95], v151, v35, v[80:95]
	v_mfma_f32_32x32x2_f32 v[96:111], v151, v43, v[96:111]
	v_mfma_f32_32x32x2_f32 v[112:127], v151, v51, v[112:127]
	v_mfma_f32_32x32x2_f32 v[64:79], v152, v28, v[64:79]
	v_mfma_f32_32x32x2_f32 v[80:95], v152, v36, v[80:95]
	v_mfma_f32_32x32x2_f32 v[96:111], v152, v44, v[96:111]
	v_mfma_f32_32x32x2_f32 v[112:127], v152, v52, v[112:127]
	v_mfma_f32_32x32x2_f32 v[64:79], v153, v29, v[64:79]
	v_mfma_f32_32x32x2_f32 v[80:95], v153, v37, v[80:95]
	v_mfma_f32_32x32x2_f32 v[96:111], v153, v45, v[96:111]
	v_mfma_f32_32x32x2_f32 v[112:127], v153, v53, v[112:127]
	v_mfma_f32_32x32x2_f32 v[64:79], v154, v30, v[64:79]
	v_mfma_f32_32x32x2_f32 v[80:95], v154, v38, v[80:95]
	v_mfma_f32_32x32x2_f32 v[96:111], v154, v46, v[96:111]
	v_mfma_f32_32x32x2_f32 v[112:127], v154, v54, v[112:127]
	v_mfma_f32_32x32x2_f32 v[64:79], v155, v31, v[64:79]
	v_mfma_f32_32x32x2_f32 v[80:95], v155, v39, v[80:95]
	v_mfma_f32_32x32x2_f32 v[96:111], v155, v47, v[96:111]
	v_mfma_f32_32x32x2_f32 v[112:127], v155, v55, v[112:127]
	s_nop 7
	s_nop 7
	s_nop 1
	v_fmac_f32_e32 v65, v64, v0
	v_fmac_f32_e32 v97, v96, v8
	v_fmac_f32_e32 v69, v68, v0
	v_fmac_f32_e32 v101, v100, v8
	v_fmac_f32_e32 v73, v72, v0
	v_fmac_f32_e32 v105, v104, v8
	v_fmac_f32_e32 v77, v76, v0
	v_fmac_f32_e32 v109, v108, v8
	v_fmac_f32_e32 v81, v64, v4
	v_fmac_f32_e32 v113, v96, v14
	v_fmac_f32_e32 v85, v68, v4
	v_fmac_f32_e32 v117, v100, v14
	v_fmac_f32_e32 v89, v72, v4
	v_fmac_f32_e32 v121, v104, v14
	v_fmac_f32_e32 v93, v76, v4
	v_fmac_f32_e32 v125, v108, v14
	v_fma_f32 v65, -v80, v4, v65
	v_fma_f32 v97, -v112, v14, v97
	v_fma_f32 v69, -v84, v4, v69
	v_fma_f32 v101, -v116, v14, v101
	v_fma_f32 v73, -v88, v4, v73
	v_fma_f32 v105, -v120, v14, v105
	v_fma_f32 v77, -v92, v4, v77
	v_fma_f32 v109, -v124, v14, v109
	v_fmac_f32_e32 v81, v80, v0
	v_fmac_f32_e32 v113, v112, v8
	v_fmac_f32_e32 v85, v84, v0
	v_fmac_f32_e32 v117, v116, v8
	v_fmac_f32_e32 v89, v88, v0
	v_fmac_f32_e32 v121, v120, v8
	v_fmac_f32_e32 v93, v92, v0
	v_fmac_f32_e32 v125, v124, v8
	v_fmac_f32_e32 v66, v65, v0
	v_fmac_f32_e32 v98, v97, v8
	v_fmac_f32_e32 v70, v69, v0
	v_fmac_f32_e32 v102, v101, v8
	v_fmac_f32_e32 v74, v73, v0
	v_fmac_f32_e32 v106, v105, v8
	v_fmac_f32_e32 v78, v77, v0
	v_fmac_f32_e32 v110, v109, v8
	v_fmac_f32_e32 v82, v65, v4
	v_fmac_f32_e32 v114, v97, v14
	v_fmac_f32_e32 v86, v69, v4
	v_fmac_f32_e32 v118, v101, v14
	v_fmac_f32_e32 v90, v73, v4
	v_fmac_f32_e32 v122, v105, v14
	v_fmac_f32_e32 v94, v77, v4
	v_fmac_f32_e32 v126, v109, v14
	v_fma_f32 v66, -v81, v4, v66
	v_fma_f32 v98, -v113, v14, v98
	v_fma_f32 v70, -v85, v4, v70
	v_fma_f32 v102, -v117, v14, v102
	v_fma_f32 v74, -v89, v4, v74
	v_fma_f32 v106, -v121, v14, v106
	v_fma_f32 v78, -v93, v4, v78
	v_fma_f32 v110, -v125, v14, v110
	v_fmac_f32_e32 v82, v81, v0
	v_fmac_f32_e32 v114, v113, v8
	v_fmac_f32_e32 v86, v85, v0
	v_fmac_f32_e32 v118, v117, v8
	v_fmac_f32_e32 v90, v89, v0
	v_fmac_f32_e32 v122, v121, v8
	v_fmac_f32_e32 v94, v93, v0
	v_fmac_f32_e32 v126, v125, v8
	v_fmac_f32_e32 v67, v66, v0
	v_fmac_f32_e32 v99, v98, v8
	v_fmac_f32_e32 v71, v70, v0
	v_fmac_f32_e32 v103, v102, v8
	v_fmac_f32_e32 v75, v74, v0
	v_fmac_f32_e32 v107, v106, v8
	v_fmac_f32_e32 v79, v78, v0
	v_fmac_f32_e32 v111, v110, v8
	v_fmac_f32_e32 v83, v66, v4
	v_fmac_f32_e32 v115, v98, v14
	v_fmac_f32_e32 v87, v70, v4
	v_fmac_f32_e32 v119, v102, v14
	v_fmac_f32_e32 v91, v74, v4
	v_fmac_f32_e32 v123, v106, v14
	v_fmac_f32_e32 v95, v78, v4
	v_fmac_f32_e32 v127, v110, v14
	v_fma_f32 v67, -v82, v4, v67
	v_fma_f32 v99, -v114, v14, v99
	v_fma_f32 v71, -v86, v4, v71
	v_fma_f32 v103, -v118, v14, v103
	v_fma_f32 v75, -v90, v4, v75
	v_fma_f32 v107, -v122, v14, v107
	v_fma_f32 v79, -v94, v4, v79
	v_fma_f32 v111, -v126, v14, v111
	v_fmac_f32_e32 v83, v82, v0
	v_fmac_f32_e32 v115, v114, v8
	v_fmac_f32_e32 v87, v86, v0
	v_fmac_f32_e32 v119, v118, v8
	v_fmac_f32_e32 v91, v90, v0
	v_fmac_f32_e32 v123, v122, v8
	v_fmac_f32_e32 v95, v94, v0
	v_fmac_f32_e32 v127, v126, v8
	v_mov_b32_e32 v158, v67
	v_mov_b32_e32 v160, v67
	v_mov_b32_e32 v159, v83
	v_mov_b32_e32 v161, v83
	v_mov_b32_e32 v164, v99
	v_mov_b32_e32 v166, v99
	v_mov_b32_e32 v165, v115
	v_mov_b32_e32 v167, v115
	s_nop 1
	v_permlane32_swap_b32_e32 v158, v160
	v_permlane32_swap_b32_e32 v159, v161
	v_permlane32_swap_b32_e32 v164, v166
	v_permlane32_swap_b32_e32 v165, v167
	v_fma_f32 v168, v128, v3, v158
	v_fma_f32 v170, v130, v11, v164
	v_fma_f32 v169, v128, v7, v159
	v_fma_f32 v171, v130, v17, v165
	v_fma_f32 v132, -v129, v7, v168
	v_fma_f32 v134, -v131, v17, v170
	v_fma_f32 v133, v129, v3, v169
	v_fma_f32 v135, v131, v11, v171
	v_cndmask_b32_e64 v136, v128, v132, s[8:9]
	v_cndmask_b32_e64 v137, v129, v133, s[8:9]
	v_cndmask_b32_e64 v156, v130, v134, s[8:9]
	v_cndmask_b32_e64 v157, v131, v135, s[8:9]
	v_fma_f32 v168, v132, v3, v160
	v_fma_f32 v170, v134, v11, v166
	v_fma_f32 v169, v132, v7, v161
	v_fma_f32 v171, v134, v17, v167
	v_fma_f32 v128, -v133, v7, v168
	v_fma_f32 v130, -v135, v17, v170
	v_fma_f32 v129, v133, v3, v169
	v_fma_f32 v131, v135, v11, v171
	v_mov_b32_e32 v246, v128
	v_mov_b32_e32 v247, v129
	v_mov_b32_e32 v248, v130
	v_mov_b32_e32 v249, v131
	v_pk_fma_f32 v[64:65], v[0:1], v[136:137], v[64:65] op_sel_hi:[1,0,1]
	v_mov_b32_e32 v158, v71
	v_pk_fma_f32 v[80:81], v[0:1], v[136:137], v[80:81] op_sel:[0,1,0]
	v_mov_b32_e32 v160, v71
	v_pk_fma_f32 v[66:67], v[2:3], v[136:137], v[66:67] op_sel_hi:[1,0,1]
	v_mov_b32_e32 v159, v87
	v_pk_fma_f32 v[82:83], v[2:3], v[136:137], v[82:83] op_sel:[0,1,0]
	v_mov_b32_e32 v161, v87
	v_pk_fma_f32 v[96:97], v[8:9], v[156:157], v[96:97] op_sel_hi:[1,0,1]
	v_mov_b32_e32 v164, v103
	v_pk_fma_f32 v[112:113], v[8:9], v[156:157], v[112:113] op_sel:[0,1,0]
	v_mov_b32_e32 v166, v103
	v_pk_fma_f32 v[98:99], v[10:11], v[156:157], v[98:99] op_sel_hi:[1,0,1]
	v_mov_b32_e32 v165, v119
	v_pk_fma_f32 v[114:115], v[10:11], v[156:157], v[114:115] op_sel:[0,1,0]
	v_mov_b32_e32 v167, v119
	v_pk_fma_f32 v[64:65], v[4:5], v[136:137], v[64:65] op_sel:[0,1,0] neg_lo:[1,0,0] neg_hi:[1,0,0]
	s_nop 1
	v_pk_fma_f32 v[80:81], v[4:5], v[136:137], v[80:81] op_sel_hi:[1,0,1]
	v_permlane32_swap_b32_e32 v158, v160
	v_pk_fma_f32 v[66:67], v[6:7], v[136:137], v[66:67] op_sel:[0,1,0] neg_lo:[1,0,0] neg_hi:[1,0,0]
	v_permlane32_swap_b32_e32 v159, v161
	v_pk_fma_f32 v[82:83], v[6:7], v[136:137], v[82:83] op_sel_hi:[1,0,1]
	v_permlane32_swap_b32_e32 v164, v166
	v_pk_fma_f32 v[96:97], v[14:15], v[156:157], v[96:97] op_sel:[0,1,0] neg_lo:[1,0,0] neg_hi:[1,0,0]
	v_permlane32_swap_b32_e32 v165, v167
	v_pk_fma_f32 v[112:113], v[14:15], v[156:157], v[112:113] op_sel_hi:[1,0,1]
	v_fma_f32 v168, v128, v3, v158
	v_pk_fma_f32 v[98:99], v[16:17], v[156:157], v[98:99] op_sel:[0,1,0] neg_lo:[1,0,0] neg_hi:[1,0,0]
	v_fma_f32 v170, v130, v11, v164
	v_pk_fma_f32 v[114:115], v[16:17], v[156:157], v[114:115] op_sel_hi:[1,0,1]
	v_fma_f32 v169, v128, v7, v159
	v_fma_f32 v171, v130, v17, v165
	v_fma_f32 v132, -v129, v7, v168
	v_fma_f32 v134, -v131, v17, v170
	v_fma_f32 v133, v129, v3, v169
	v_fma_f32 v135, v131, v11, v171
	v_cndmask_b32_e64 v172, v128, v132, s[8:9]
	v_cndmask_b32_e64 v173, v129, v133, s[8:9]
	v_cndmask_b32_e64 v244, v130, v134, s[8:9]
	v_cndmask_b32_e64 v245, v131, v135, s[8:9]
	v_fma_f32 v168, v132, v3, v160
	v_fma_f32 v170, v134, v11, v166
	v_fma_f32 v169, v132, v7, v161
	v_fma_f32 v171, v134, v17, v167
	v_fma_f32 v128, -v133, v7, v168
	v_fma_f32 v130, -v135, v17, v170
	v_fma_f32 v129, v133, v3, v169
	v_fma_f32 v131, v135, v11, v171
	v_pk_fma_f32 v[68:69], v[0:1], v[172:173], v[68:69] op_sel_hi:[1,0,1]
	v_mov_b32_e32 v158, v75
	v_pk_fma_f32 v[84:85], v[0:1], v[172:173], v[84:85] op_sel:[0,1,0]
	v_mov_b32_e32 v160, v75
	v_pk_fma_f32 v[70:71], v[2:3], v[172:173], v[70:71] op_sel_hi:[1,0,1]
	v_mov_b32_e32 v159, v91
	v_pk_fma_f32 v[86:87], v[2:3], v[172:173], v[86:87] op_sel:[0,1,0]
	v_mov_b32_e32 v161, v91
	v_pk_fma_f32 v[100:101], v[8:9], v[244:245], v[100:101] op_sel_hi:[1,0,1]
	v_mov_b32_e32 v164, v107
	v_pk_fma_f32 v[116:117], v[8:9], v[244:245], v[116:117] op_sel:[0,1,0]
	v_mov_b32_e32 v166, v107
	v_pk_fma_f32 v[102:103], v[10:11], v[244:245], v[102:103] op_sel_hi:[1,0,1]
	v_mov_b32_e32 v165, v123
	v_pk_fma_f32 v[118:119], v[10:11], v[244:245], v[118:119] op_sel:[0,1,0]
	v_mov_b32_e32 v167, v123
	v_pk_fma_f32 v[68:69], v[4:5], v[172:173], v[68:69] op_sel:[0,1,0] neg_lo:[1,0,0] neg_hi:[1,0,0]
	s_nop 1
	v_pk_fma_f32 v[84:85], v[4:5], v[172:173], v[84:85] op_sel_hi:[1,0,1]
	v_permlane32_swap_b32_e32 v158, v160
	v_pk_fma_f32 v[70:71], v[6:7], v[172:173], v[70:71] op_sel:[0,1,0] neg_lo:[1,0,0] neg_hi:[1,0,0]
	v_permlane32_swap_b32_e32 v159, v161
	v_pk_fma_f32 v[86:87], v[6:7], v[172:173], v[86:87] op_sel_hi:[1,0,1]
	v_permlane32_swap_b32_e32 v164, v166
	v_pk_fma_f32 v[100:101], v[14:15], v[244:245], v[100:101] op_sel:[0,1,0] neg_lo:[1,0,0] neg_hi:[1,0,0]
	v_permlane32_swap_b32_e32 v165, v167
	v_pk_fma_f32 v[116:117], v[14:15], v[244:245], v[116:117] op_sel_hi:[1,0,1]
	v_fma_f32 v168, v128, v3, v158
	v_pk_fma_f32 v[102:103], v[16:17], v[244:245], v[102:103] op_sel:[0,1,0] neg_lo:[1,0,0] neg_hi:[1,0,0]
	v_fma_f32 v170, v130, v11, v164
	v_pk_fma_f32 v[118:119], v[16:17], v[244:245], v[118:119] op_sel_hi:[1,0,1]
	v_fma_f32 v169, v128, v7, v159
	v_fma_f32 v171, v130, v17, v165
	v_fma_f32 v132, -v129, v7, v168
	v_fma_f32 v134, -v131, v17, v170
	v_fma_f32 v133, v129, v3, v169
	v_fma_f32 v135, v131, v11, v171
	v_cndmask_b32_e64 v136, v128, v132, s[8:9]
	v_cndmask_b32_e64 v137, v129, v133, s[8:9]
	v_cndmask_b32_e64 v156, v130, v134, s[8:9]
	v_cndmask_b32_e64 v157, v131, v135, s[8:9]
	v_fma_f32 v168, v132, v3, v160
	v_fma_f32 v170, v134, v11, v166
	v_fma_f32 v169, v132, v7, v161
	v_fma_f32 v171, v134, v17, v167
	v_fma_f32 v128, -v133, v7, v168
	v_fma_f32 v130, -v135, v17, v170
	v_fma_f32 v129, v133, v3, v169
	v_fma_f32 v131, v135, v11, v171
	v_pk_fma_f32 v[72:73], v[0:1], v[136:137], v[72:73] op_sel_hi:[1,0,1]
	v_mov_b32_e32 v158, v79
	v_pk_fma_f32 v[88:89], v[0:1], v[136:137], v[88:89] op_sel:[0,1,0]
	v_mov_b32_e32 v160, v79
	v_pk_fma_f32 v[74:75], v[2:3], v[136:137], v[74:75] op_sel_hi:[1,0,1]
	v_mov_b32_e32 v159, v95
	v_pk_fma_f32 v[90:91], v[2:3], v[136:137], v[90:91] op_sel:[0,1,0]
	v_mov_b32_e32 v161, v95
	v_pk_fma_f32 v[104:105], v[8:9], v[156:157], v[104:105] op_sel_hi:[1,0,1]
	v_mov_b32_e32 v164, v111
	v_pk_fma_f32 v[120:121], v[8:9], v[156:157], v[120:121] op_sel:[0,1,0]
	v_mov_b32_e32 v166, v111
	v_pk_fma_f32 v[106:107], v[10:11], v[156:157], v[106:107] op_sel_hi:[1,0,1]
	v_mov_b32_e32 v165, v127
	v_pk_fma_f32 v[122:123], v[10:11], v[156:157], v[122:123] op_sel:[0,1,0]
	v_mov_b32_e32 v167, v127
	v_pk_fma_f32 v[72:73], v[4:5], v[136:137], v[72:73] op_sel:[0,1,0] neg_lo:[1,0,0] neg_hi:[1,0,0]
	s_nop 1
	v_pk_fma_f32 v[88:89], v[4:5], v[136:137], v[88:89] op_sel_hi:[1,0,1]
	v_permlane32_swap_b32_e32 v158, v160
	v_pk_fma_f32 v[74:75], v[6:7], v[136:137], v[74:75] op_sel:[0,1,0] neg_lo:[1,0,0] neg_hi:[1,0,0]
	v_permlane32_swap_b32_e32 v159, v161
	v_pk_fma_f32 v[90:91], v[6:7], v[136:137], v[90:91] op_sel_hi:[1,0,1]
	v_permlane32_swap_b32_e32 v164, v166
	v_pk_fma_f32 v[104:105], v[14:15], v[156:157], v[104:105] op_sel:[0,1,0] neg_lo:[1,0,0] neg_hi:[1,0,0]
	v_permlane32_swap_b32_e32 v165, v167
	v_pk_fma_f32 v[120:121], v[14:15], v[156:157], v[120:121] op_sel_hi:[1,0,1]
	v_fma_f32 v168, v128, v3, v158
	v_pk_fma_f32 v[106:107], v[16:17], v[156:157], v[106:107] op_sel:[0,1,0] neg_lo:[1,0,0] neg_hi:[1,0,0]
	v_fma_f32 v170, v130, v11, v164
	v_pk_fma_f32 v[122:123], v[16:17], v[156:157], v[122:123] op_sel_hi:[1,0,1]
	v_fma_f32 v169, v128, v7, v159
	v_fma_f32 v171, v130, v17, v165
	v_fma_f32 v132, -v129, v7, v168
	v_fma_f32 v134, -v131, v17, v170
	v_fma_f32 v133, v129, v3, v169
	v_fma_f32 v135, v131, v11, v171
	v_cndmask_b32_e64 v172, v128, v132, s[8:9]
	v_cndmask_b32_e64 v173, v129, v133, s[8:9]
	v_cndmask_b32_e64 v244, v130, v134, s[8:9]
	v_cndmask_b32_e64 v245, v131, v135, s[8:9]
	v_fma_f32 v168, v132, v3, v160
	v_fma_f32 v170, v134, v11, v166
	v_fma_f32 v169, v132, v7, v161
	v_fma_f32 v171, v134, v17, v167
	v_fma_f32 v128, -v133, v7, v168
	v_fma_f32 v130, -v135, v17, v170
	v_fma_f32 v129, v133, v3, v169
	v_fma_f32 v131, v135, v11, v171
	v_pk_fma_f32 v[76:77], v[0:1], v[172:173], v[76:77] op_sel_hi:[1,0,1]
	v_pk_fma_f32 v[92:93], v[0:1], v[172:173], v[92:93] op_sel:[0,1,0]
	v_pk_fma_f32 v[78:79], v[2:3], v[172:173], v[78:79] op_sel_hi:[1,0,1]
	v_pk_fma_f32 v[94:95], v[2:3], v[172:173], v[94:95] op_sel:[0,1,0]
	v_pk_fma_f32 v[108:109], v[8:9], v[244:245], v[108:109] op_sel_hi:[1,0,1]
	v_pk_fma_f32 v[124:125], v[8:9], v[244:245], v[124:125] op_sel:[0,1,0]
	v_pk_fma_f32 v[110:111], v[10:11], v[244:245], v[110:111] op_sel_hi:[1,0,1]
	v_pk_fma_f32 v[126:127], v[10:11], v[244:245], v[126:127] op_sel:[0,1,0]
	v_pk_fma_f32 v[76:77], v[4:5], v[172:173], v[76:77] op_sel:[0,1,0] neg_lo:[1,0,0] neg_hi:[1,0,0]
	v_pk_fma_f32 v[92:93], v[4:5], v[172:173], v[92:93] op_sel_hi:[1,0,1]
	v_pk_fma_f32 v[78:79], v[6:7], v[172:173], v[78:79] op_sel:[0,1,0] neg_lo:[1,0,0] neg_hi:[1,0,0]
	v_pk_fma_f32 v[94:95], v[6:7], v[172:173], v[94:95] op_sel_hi:[1,0,1]
	v_pk_fma_f32 v[108:109], v[14:15], v[244:245], v[108:109] op_sel:[0,1,0] neg_lo:[1,0,0] neg_hi:[1,0,0]
	v_pk_fma_f32 v[124:125], v[14:15], v[244:245], v[124:125] op_sel_hi:[1,0,1]
	v_pk_fma_f32 v[110:111], v[16:17], v[244:245], v[110:111] op_sel:[0,1,0] neg_lo:[1,0,0] neg_hi:[1,0,0]
	v_pk_fma_f32 v[126:127], v[16:17], v[244:245], v[126:127] op_sel_hi:[1,0,1]
	v_cvt_pk_bf16_f32 v56, v64, v80
	ds_write_b32 v229, v56 offset:0
	v_cvt_pk_bf16_f32 v57, v96, v112
	ds_write_b32 v229, v57 offset:128
	v_cvt_pk_bf16_f32 v58, v65, v81
	ds_write_b32 v229, v58 offset:272
	v_cvt_pk_bf16_f32 v59, v97, v113
	ds_write_b32 v229, v59 offset:400
	v_cvt_pk_bf16_f32 v56, v66, v82
	ds_write_b32 v229, v56 offset:544
	v_cvt_pk_bf16_f32 v57, v98, v114
	ds_write_b32 v229, v57 offset:672
	v_cvt_pk_bf16_f32 v58, v67, v83
	ds_write_b32 v229, v58 offset:816
	v_cvt_pk_bf16_f32 v59, v99, v115
	ds_write_b32 v229, v59 offset:944
	v_cvt_pk_bf16_f32 v56, v68, v84
	ds_write_b32 v229, v56 offset:2176
	v_cvt_pk_bf16_f32 v57, v100, v116
	ds_write_b32 v229, v57 offset:2304
	v_cvt_pk_bf16_f32 v58, v69, v85
	ds_write_b32 v229, v58 offset:2448
	v_cvt_pk_bf16_f32 v59, v101, v117
	ds_write_b32 v229, v59 offset:2576
	v_cvt_pk_bf16_f32 v56, v70, v86
	ds_write_b32 v229, v56 offset:2720
	v_cvt_pk_bf16_f32 v57, v102, v118
	ds_write_b32 v229, v57 offset:2848
	v_cvt_pk_bf16_f32 v58, v71, v87
	ds_write_b32 v229, v58 offset:2992
	v_cvt_pk_bf16_f32 v59, v103, v119
	ds_write_b32 v229, v59 offset:3120
	v_cvt_pk_bf16_f32 v56, v72, v88
	ds_write_b32 v229, v56 offset:4352
	v_cvt_pk_bf16_f32 v57, v104, v120
	ds_write_b32 v229, v57 offset:4480
	v_cvt_pk_bf16_f32 v58, v73, v89
	ds_write_b32 v229, v58 offset:4624
	v_cvt_pk_bf16_f32 v59, v105, v121
	ds_write_b32 v229, v59 offset:4752
	v_cvt_pk_bf16_f32 v56, v74, v90
	ds_write_b32 v229, v56 offset:4896
	v_cvt_pk_bf16_f32 v57, v106, v122
	ds_write_b32 v229, v57 offset:5024
	v_cvt_pk_bf16_f32 v58, v75, v91
	ds_write_b32 v229, v58 offset:5168
	v_cvt_pk_bf16_f32 v59, v107, v123
	ds_write_b32 v229, v59 offset:5296
	v_cvt_pk_bf16_f32 v56, v76, v92
	ds_write_b32 v229, v56 offset:6528
	v_cvt_pk_bf16_f32 v57, v108, v124
	ds_write_b32 v229, v57 offset:6656
	v_cvt_pk_bf16_f32 v58, v77, v93
	ds_write_b32 v229, v58 offset:6800
	v_cvt_pk_bf16_f32 v59, v109, v125
	ds_write_b32 v229, v59 offset:6928
	v_cvt_pk_bf16_f32 v56, v78, v94
	ds_write_b32 v229, v56 offset:7072
	v_cvt_pk_bf16_f32 v57, v110, v126
	ds_write_b32 v229, v57 offset:7200
	v_cvt_pk_bf16_f32 v58, v79, v95
	ds_write_b32 v229, v58 offset:7344
	v_cvt_pk_bf16_f32 v59, v111, v127
	ds_write_b32 v229, v59 offset:7472
	s_cmp_eq_u32 s83, s82
	s_cbranch_scc1 .Ls5b_nopf
	s_lshl_b32 s67, s83, 3
	s_add_i32 s67, s67, s77
	s_add_i32 s67, s67, 0xf680
	s_mul_hi_u32 s65, s67, 0x2ad5802b
	s_lshr_b32 s65, s65, 8
	s_mul_i32 s66, s65, 0x5fa
	s_sub_i32 s66, s67, s66
	s_lshl_b32 s66, s66, 13
	s_and_b32 s32, s65, 31
	s_mul_i32 s32, s32, 0xc00000
	s_add_i32 s66, s66, s32
	v_readfirstlane_b32 s84, v235
	v_readfirstlane_b32 s85, v236
	v_readfirstlane_b32 s4, v237
	v_readfirstlane_b32 s6, v238
	v_readfirstlane_b32 s100, v239
	v_readfirstlane_b32 s101, v240
	s_cmp_lt_u32 s65, 32
	s_cselect_b32 s84, s84, s4
	s_cselect_b32 s85, s85, s6
	s_mov_b32 s32, 0x1f210000
	s_cselect_b32 s32, 0x7210000, s32
	s_add_u32 s84, s84, s66
	s_addc_u32 s85, s85, 0
	s_add_u32 s84, s84, 0xc000
	s_addc_u32 s85, s85, 0
	s_add_u32 s32, s32, s66
	s_add_u32 s100, s100, s32
	s_addc_u32 s101, s101, 0
	global_load_dwordx4 v[96:99], v13, s[84:85] nt
	global_load_dwordx4 v[100:103], v13, s[84:85] offset:1024 nt
	global_load_dwordx4 v[104:107], v13, s[84:85] offset:2048 nt
	global_load_dwordx4 v[108:111], v13, s[84:85] offset:3072 nt
	global_load_dwordx4 v[112:115], v21, s[84:85] nt
	global_load_dwordx4 v[116:119], v21, s[84:85] offset:1024 nt
	global_load_dwordx4 v[120:123], v21, s[84:85] offset:2048 nt
	global_load_dwordx4 v[124:127], v21, s[84:85] offset:3072 nt

.LBB0_412:
	s_cmp_lt_u32 s33, 64
	s_cbranch_scc1 .Lcpyb_end
	v_lshrrev_b32_e32 v21, 6, v174
	v_and_b32_e32 v22, 63, v174
	v_lshlrev_b32_e32 v22, 4, v22
	v_readfirstlane_b32 s80, v21
	v_add_u32_e32 v23, 0x1000, v22
	v_readfirstlane_b32 s92, v235
	v_readfirstlane_b32 s93, v236
	v_readfirstlane_b32 s94, v237
	v_readfirstlane_b32 s95, v238
	v_readfirstlane_b32 s98, v239
	v_readfirstlane_b32 s99, v240
	s_add_i32 s80, s80, s33
	s_add_i32 s80, s80, 0x25f0
	s_sub_i32 s100, s78, 8
	s_lshl_b32 s100, s100, 3
.Lcpyb_loop:
	s_add_i32 s101, s80, s100
	s_cmp_lt_u32 s101, 0x5510
	s_cbranch_scc0 .Lcpyb_tail
	s_mul_hi_u32 s81, s80, 0x2ad5802b
	s_lshr_b32 s81, s81, 8
	s_mul_i32 s82, s81, 0x5fa
	s_sub_i32 s82, s80, s82
	s_lshl_b32 s82, s82, 13
	s_and_b32 s83, s81, 31
	s_mul_i32 s83, s83, 0xc00000
	s_add_i32 s82, s82, s83
	s_cmp_lt_u32 s81, 32
	s_cselect_b32 s84, s92, s94
	s_cselect_b32 s85, s93, s95
	s_mov_b32 s83, 0x1f210000
	s_cselect_b32 s83, 0x7210000, s83
	s_add_u32 s84, s84, s82
	s_addc_u32 s85, s85, 0
	s_add_u32 s84, s84, 0xc000
	s_addc_u32 s85, s85, 0
	s_add_u32 s83, s83, s82
	s_add_u32 s86, s98, s83
	s_addc_u32 s87, s99, 0
	s_mul_hi_u32 s81, s101, 0x2ad5802b
	s_lshr_b32 s81, s81, 8
	s_mul_i32 s82, s81, 0x5fa
	s_sub_i32 s82, s101, s82
	s_lshl_b32 s82, s82, 13
	s_and_b32 s83, s81, 31
	s_mul_i32 s83, s83, 0xc00000
	s_add_i32 s82, s82, s83
	s_cmp_lt_u32 s81, 32
	s_cselect_b32 s88, s92, s94
	s_cselect_b32 s89, s93, s95
	s_mov_b32 s83, 0x1f210000
	s_cselect_b32 s83, 0x7210000, s83
	s_add_u32 s88, s88, s82
	s_addc_u32 s89, s89, 0
	s_add_u32 s88, s88, 0xc000
	s_addc_u32 s89, s89, 0
	s_add_u32 s83, s83, s82
	s_add_u32 s90, s98, s83
	s_addc_u32 s91, s99, 0
	global_load_dwordx4 v[64:67], v22, s[84:85] nt
	global_load_dwordx4 v[68:71], v22, s[84:85] offset:1024 nt
	global_load_dwordx4 v[72:75], v22, s[84:85] offset:2048 nt
	global_load_dwordx4 v[76:79], v22, s[84:85] offset:3072 nt
	global_load_dwordx4 v[80:83], v23, s[84:85] nt
	global_load_dwordx4 v[84:87], v23, s[84:85] offset:1024 nt
	global_load_dwordx4 v[88:91], v23, s[84:85] offset:2048 nt
	global_load_dwordx4 v[92:95], v23, s[84:85] offset:3072 nt
	global_load_dwordx4 v[96:99], v22, s[88:89] nt
	global_load_dwordx4 v[100:103], v22, s[88:89] offset:1024 nt
	global_load_dwordx4 v[104:107], v22, s[88:89] offset:2048 nt
	global_load_dwordx4 v[108:111], v22, s[88:89] offset:3072 nt
	global_load_dwordx4 v[112:115], v23, s[88:89] nt
	global_load_dwordx4 v[116:119], v23, s[88:89] offset:1024 nt
	global_load_dwordx4 v[120:123], v23, s[88:89] offset:2048 nt
	global_load_dwordx4 v[124:127], v23, s[88:89] offset:3072 nt
	s_waitcnt vmcnt(15)
	global_store_dwordx4 v22, v[64:67], s[86:87] nt
	s_waitcnt vmcnt(15)
	global_store_dwordx4 v22, v[68:71], s[86:87] offset:1024 nt
	s_waitcnt vmcnt(15)
	global_store_dwordx4 v22, v[72:75], s[86:87] offset:2048 nt
	s_waitcnt vmcnt(15)
	global_store_dwordx4 v22, v[76:79], s[86:87] offset:3072 nt
	s_waitcnt vmcnt(15)
	global_store_dwordx4 v23, v[80:83], s[86:87] nt
	s_waitcnt vmcnt(15)
	global_store_dwordx4 v23, v[84:87], s[86:87] offset:1024 nt
	s_waitcnt vmcnt(15)
	global_store_dwordx4 v23, v[88:91], s[86:87] offset:2048 nt
	s_waitcnt vmcnt(15)
	global_store_dwordx4 v23, v[92:95], s[86:87] offset:3072 nt
	s_waitcnt vmcnt(15)
	global_store_dwordx4 v22, v[96:99], s[90:91] nt
	s_waitcnt vmcnt(15)
	global_store_dwordx4 v22, v[100:103], s[90:91] offset:1024 nt
	s_waitcnt vmcnt(15)
	global_store_dwordx4 v22, v[104:107], s[90:91] offset:2048 nt
	s_waitcnt vmcnt(15)
	global_store_dwordx4 v22, v[108:111], s[90:91] offset:3072 nt
	s_waitcnt vmcnt(15)
	global_store_dwordx4 v23, v[112:115], s[90:91] nt
	s_waitcnt vmcnt(15)
	global_store_dwordx4 v23, v[116:119], s[90:91] offset:1024 nt
	s_waitcnt vmcnt(15)
	global_store_dwordx4 v23, v[120:123], s[90:91] offset:2048 nt
	s_waitcnt vmcnt(15)
	global_store_dwordx4 v23, v[124:127], s[90:91] offset:3072 nt
	s_add_i32 s80, s101, s100
	s_branch .Lcpyb_loop
.Lcpyb_tail:
	s_cmp_lt_u32 s80, 0x5510
	s_cbranch_scc0 .Lcpyb_end
	s_mul_hi_u32 s81, s80, 0x2ad5802b
	s_lshr_b32 s81, s81, 8
	s_mul_i32 s82, s81, 0x5fa
	s_sub_i32 s82, s80, s82
	s_lshl_b32 s82, s82, 13
	s_and_b32 s83, s81, 31
	s_mul_i32 s83, s83, 0xc00000
	s_add_i32 s82, s82, s83
	s_cmp_lt_u32 s81, 32
	s_cselect_b32 s84, s92, s94
	s_cselect_b32 s85, s93, s95
	s_mov_b32 s83, 0x1f210000
	s_cselect_b32 s83, 0x7210000, s83
	s_add_u32 s84, s84, s82
	s_addc_u32 s85, s85, 0
	s_add_u32 s84, s84, 0xc000
	s_addc_u32 s85, s85, 0
	s_add_u32 s83, s83, s82
	s_add_u32 s86, s98, s83
	s_addc_u32 s87, s99, 0
	global_load_dwordx4 v[64:67], v22, s[84:85] nt
	global_load_dwordx4 v[68:71], v22, s[84:85] offset:1024 nt
	global_load_dwordx4 v[72:75], v22, s[84:85] offset:2048 nt
	global_load_dwordx4 v[76:79], v22, s[84:85] offset:3072 nt
	global_load_dwordx4 v[80:83], v23, s[84:85] nt
	global_load_dwordx4 v[84:87], v23, s[84:85] offset:1024 nt
	global_load_dwordx4 v[88:91], v23, s[84:85] offset:2048 nt
	global_load_dwordx4 v[92:95], v23, s[84:85] offset:3072 nt
	s_waitcnt vmcnt(7)
	global_store_dwordx4 v22, v[64:67], s[86:87] nt
	s_waitcnt vmcnt(7)
	global_store_dwordx4 v22, v[68:71], s[86:87] offset:1024 nt
	s_waitcnt vmcnt(7)
	global_store_dwordx4 v22, v[72:75], s[86:87] offset:2048 nt
	s_waitcnt vmcnt(7)
	global_store_dwordx4 v22, v[76:79], s[86:87] offset:3072 nt
	s_waitcnt vmcnt(7)
	global_store_dwordx4 v23, v[80:83], s[86:87] nt
	s_waitcnt vmcnt(7)
	global_store_dwordx4 v23, v[84:87], s[86:87] offset:1024 nt
	s_waitcnt vmcnt(7)
	global_store_dwordx4 v23, v[88:91], s[86:87] offset:2048 nt
	s_waitcnt vmcnt(7)
	global_store_dwordx4 v23, v[92:95], s[86:87] offset:3072 nt

.LBB0_452:
	s_cmp_lt_u32 s33, 1200
	s_cbranch_scc1 .Lcpyc_end
	v_lshrrev_b32_e32 v21, 6, v174
	v_and_b32_e32 v22, 63, v174
	v_lshlrev_b32_e32 v22, 4, v22
	v_readfirstlane_b32 s80, v21
	v_add_u32_e32 v23, 0x1000, v22
	v_readfirstlane_b32 s92, v235
	v_readfirstlane_b32 s93, v236
	v_readfirstlane_b32 s94, v237
	v_readfirstlane_b32 s95, v238
	v_readfirstlane_b32 s98, v239
	v_readfirstlane_b32 s99, v240
	s_add_i32 s80, s80, s33
	s_add_i32 s80, s80, 0x5060
	s_sub_i32 s100, s78, 150
	s_lshl_b32 s100, s100, 3
.Lcpyc_loop:
	s_add_i32 s101, s80, s100
	s_cmp_lt_u32 s101, 0x7450
	s_cbranch_scc0 .Lcpyc_tail
	s_mul_hi_u32 s81, s80, 0x2ad5802b
	s_lshr_b32 s81, s81, 8
	s_mul_i32 s82, s81, 0x5fa
	s_sub_i32 s82, s80, s82
	s_lshl_b32 s82, s82, 13
	s_and_b32 s83, s81, 31
	s_mul_i32 s83, s83, 0xc00000
	s_add_i32 s82, s82, s83
	s_cmp_lt_u32 s81, 32
	s_cselect_b32 s84, s92, s94
	s_cselect_b32 s85, s93, s95
	s_mov_b32 s83, 0x1f210000
	s_cselect_b32 s83, 0x7210000, s83
	s_add_u32 s84, s84, s82
	s_addc_u32 s85, s85, 0
	s_add_u32 s84, s84, 0xc000
	s_addc_u32 s85, s85, 0
	s_add_u32 s83, s83, s82
	s_add_u32 s86, s98, s83
	s_addc_u32 s87, s99, 0
	s_mul_hi_u32 s81, s101, 0x2ad5802b
	s_lshr_b32 s81, s81, 8
	s_mul_i32 s82, s81, 0x5fa
	s_sub_i32 s82, s101, s82
	s_lshl_b32 s82, s82, 13
	s_and_b32 s83, s81, 31
	s_mul_i32 s83, s83, 0xc00000
	s_add_i32 s82, s82, s83
	s_cmp_lt_u32 s81, 32
	s_cselect_b32 s88, s92, s94
	s_cselect_b32 s89, s93, s95
	s_mov_b32 s83, 0x1f210000
	s_cselect_b32 s83, 0x7210000, s83
	s_add_u32 s88, s88, s82
	s_addc_u32 s89, s89, 0
	s_add_u32 s88, s88, 0xc000
	s_addc_u32 s89, s89, 0
	s_add_u32 s83, s83, s82
	s_add_u32 s90, s98, s83
	s_addc_u32 s91, s99, 0
	global_load_dwordx4 v[64:67], v22, s[84:85] nt
	global_load_dwordx4 v[68:71], v22, s[84:85] offset:1024 nt
	global_load_dwordx4 v[72:75], v22, s[84:85] offset:2048 nt
	global_load_dwordx4 v[76:79], v22, s[84:85] offset:3072 nt
	global_load_dwordx4 v[80:83], v23, s[84:85] nt
	global_load_dwordx4 v[84:87], v23, s[84:85] offset:1024 nt
	global_load_dwordx4 v[88:91], v23, s[84:85] offset:2048 nt
	global_load_dwordx4 v[92:95], v23, s[84:85] offset:3072 nt
	global_load_dwordx4 v[96:99], v22, s[88:89] nt
	global_load_dwordx4 v[100:103], v22, s[88:89] offset:1024 nt
	global_load_dwordx4 v[104:107], v22, s[88:89] offset:2048 nt
	global_load_dwordx4 v[108:111], v22, s[88:89] offset:3072 nt
	global_load_dwordx4 v[112:115], v23, s[88:89] nt
	global_load_dwordx4 v[116:119], v23, s[88:89] offset:1024 nt
	global_load_dwordx4 v[120:123], v23, s[88:89] offset:2048 nt
	global_load_dwordx4 v[124:127], v23, s[88:89] offset:3072 nt
	s_waitcnt vmcnt(15)
	global_store_dwordx4 v22, v[64:67], s[86:87] nt
	s_waitcnt vmcnt(15)
	global_store_dwordx4 v22, v[68:71], s[86:87] offset:1024 nt
	s_waitcnt vmcnt(15)
	global_store_dwordx4 v22, v[72:75], s[86:87] offset:2048 nt
	s_waitcnt vmcnt(15)
	global_store_dwordx4 v22, v[76:79], s[86:87] offset:3072 nt
	s_waitcnt vmcnt(15)
	global_store_dwordx4 v23, v[80:83], s[86:87] nt
	s_waitcnt vmcnt(15)
	global_store_dwordx4 v23, v[84:87], s[86:87] offset:1024 nt
	s_waitcnt vmcnt(15)
	global_store_dwordx4 v23, v[88:91], s[86:87] offset:2048 nt
	s_waitcnt vmcnt(15)
	global_store_dwordx4 v23, v[92:95], s[86:87] offset:3072 nt
	s_waitcnt vmcnt(15)
	global_store_dwordx4 v22, v[96:99], s[90:91] nt
	s_waitcnt vmcnt(15)
	global_store_dwordx4 v22, v[100:103], s[90:91] offset:1024 nt
	s_waitcnt vmcnt(15)
	global_store_dwordx4 v22, v[104:107], s[90:91] offset:2048 nt
	s_waitcnt vmcnt(15)
	global_store_dwordx4 v22, v[108:111], s[90:91] offset:3072 nt
	s_waitcnt vmcnt(15)
	global_store_dwordx4 v23, v[112:115], s[90:91] nt
	s_waitcnt vmcnt(15)
	global_store_dwordx4 v23, v[116:119], s[90:91] offset:1024 nt
	s_waitcnt vmcnt(15)
	global_store_dwordx4 v23, v[120:123], s[90:91] offset:2048 nt
	s_waitcnt vmcnt(15)
	global_store_dwordx4 v23, v[124:127], s[90:91] offset:3072 nt
	s_add_i32 s80, s101, s100
	s_branch .Lcpyc_loop
.Lcpyc_tail:
	s_cmp_lt_u32 s80, 0x7450
	s_cbranch_scc0 .Lcpyc_end
	s_mul_hi_u32 s81, s80, 0x2ad5802b
	s_lshr_b32 s81, s81, 8
	s_mul_i32 s82, s81, 0x5fa
	s_sub_i32 s82, s80, s82
	s_lshl_b32 s82, s82, 13
	s_and_b32 s83, s81, 31
	s_mul_i32 s83, s83, 0xc00000
	s_add_i32 s82, s82, s83
	s_cmp_lt_u32 s81, 32
	s_cselect_b32 s84, s92, s94
	s_cselect_b32 s85, s93, s95
	s_mov_b32 s83, 0x1f210000
	s_cselect_b32 s83, 0x7210000, s83
	s_add_u32 s84, s84, s82
	s_addc_u32 s85, s85, 0
	s_add_u32 s84, s84, 0xc000
	s_addc_u32 s85, s85, 0
	s_add_u32 s83, s83, s82
	s_add_u32 s86, s98, s83
	s_addc_u32 s87, s99, 0
	global_load_dwordx4 v[64:67], v22, s[84:85] nt
	global_load_dwordx4 v[68:71], v22, s[84:85] offset:1024 nt
	global_load_dwordx4 v[72:75], v22, s[84:85] offset:2048 nt
	global_load_dwordx4 v[76:79], v22, s[84:85] offset:3072 nt
	global_load_dwordx4 v[80:83], v23, s[84:85] nt
	global_load_dwordx4 v[84:87], v23, s[84:85] offset:1024 nt
	global_load_dwordx4 v[88:91], v23, s[84:85] offset:2048 nt
	global_load_dwordx4 v[92:95], v23, s[84:85] offset:3072 nt
	s_waitcnt vmcnt(7)
	global_store_dwordx4 v22, v[64:67], s[86:87] nt
	s_waitcnt vmcnt(7)
	global_store_dwordx4 v22, v[68:71], s[86:87] offset:1024 nt
	s_waitcnt vmcnt(7)
	global_store_dwordx4 v22, v[72:75], s[86:87] offset:2048 nt
	s_waitcnt vmcnt(7)
	global_store_dwordx4 v22, v[76:79], s[86:87] offset:3072 nt
	s_waitcnt vmcnt(7)
	global_store_dwordx4 v23, v[80:83], s[86:87] nt
	s_waitcnt vmcnt(7)
	global_store_dwordx4 v23, v[84:87], s[86:87] offset:1024 nt
	s_waitcnt vmcnt(7)
	global_store_dwordx4 v23, v[88:91], s[86:87] offset:2048 nt
	s_waitcnt vmcnt(7)
	global_store_dwordx4 v23, v[92:95], s[86:87] offset:3072 nt

.LBB0_472:
	s_or_b64 exec, exec, s[8:9]
	v_readlane_b32 s4, v234, 2
	v_mov_b32_e32 v8, v174
	v_readlane_b32 s5, v234, 3
	s_barrier
	s_and_b32 s80, s33, 64
	s_cmp_eq_u32 s80, 0
	s_cbranch_scc1 .Lpre2_skip
	v_lshrrev_b32_e32 v21, 6, v174
	v_and_b32_e32 v22, 63, v174
	v_lshlrev_b32_e32 v22, 4, v22
	v_readfirstlane_b32 s80, v21
	v_add_u32_e32 v23, 0x1000, v22
	v_readfirstlane_b32 s92, v235
	v_readfirstlane_b32 s93, v236
	v_readfirstlane_b32 s94, v237
	v_readfirstlane_b32 s95, v238
	v_readfirstlane_b32 s98, v239
	v_readfirstlane_b32 s99, v240
	s_lshr_b32 s100, s33, 7
	s_lshl_b32 s100, s100, 3
	s_lshr_b32 s101, s33, 3
	s_and_b32 s101, s101, 7
	s_add_i32 s100, s100, s101
	s_lshl_b32 s100, s100, 3
	s_add_i32 s80, s80, s100
	s_add_i32 s80, s80, 0x7450
	s_movk_i32 s100, 0x400
.Lcpy2p_loop:
	s_add_i32 s101, s80, s100
	s_cmp_lt_u32 s101, 0x7984
	s_cbranch_scc0 .Lcpy2p_tail
	s_mul_hi_u32 s81, s80, 0x2ad5802b
	s_lshr_b32 s81, s81, 8
	s_mul_i32 s82, s81, 0x5fa
	s_sub_i32 s82, s80, s82
	s_lshl_b32 s82, s82, 13
	s_and_b32 s83, s81, 31
	s_mul_i32 s83, s83, 0xc00000
	s_add_i32 s82, s82, s83
	s_cmp_lt_u32 s81, 32
	s_cselect_b32 s84, s92, s94
	s_cselect_b32 s85, s93, s95
	s_mov_b32 s83, 0x1f210000
	s_cselect_b32 s83, 0x7210000, s83
	s_add_u32 s84, s84, s82
	s_addc_u32 s85, s85, 0
	s_add_u32 s84, s84, 0xc000
	s_addc_u32 s85, s85, 0
	s_add_u32 s83, s83, s82
	s_add_u32 s86, s98, s83
	s_addc_u32 s87, s99, 0
	s_mul_hi_u32 s81, s101, 0x2ad5802b
	s_lshr_b32 s81, s81, 8
	s_mul_i32 s82, s81, 0x5fa
	s_sub_i32 s82, s101, s82
	s_lshl_b32 s82, s82, 13
	s_and_b32 s83, s81, 31
	s_mul_i32 s83, s83, 0xc00000
	s_add_i32 s82, s82, s83
	s_cmp_lt_u32 s81, 32
	s_cselect_b32 s88, s92, s94
	s_cselect_b32 s89, s93, s95
	s_mov_b32 s83, 0x1f210000
	s_cselect_b32 s83, 0x7210000, s83
	s_add_u32 s88, s88, s82
	s_addc_u32 s89, s89, 0
	s_add_u32 s88, s88, 0xc000
	s_addc_u32 s89, s89, 0
	s_add_u32 s83, s83, s82
	s_add_u32 s90, s98, s83
	s_addc_u32 s91, s99, 0
	global_load_dwordx4 v[64:67], v22, s[84:85] nt
	global_load_dwordx4 v[68:71], v22, s[84:85] offset:1024 nt
	global_load_dwordx4 v[72:75], v22, s[84:85] offset:2048 nt
	global_load_dwordx4 v[76:79], v22, s[84:85] offset:3072 nt
	global_load_dwordx4 v[80:83], v23, s[84:85] nt
	global_load_dwordx4 v[84:87], v23, s[84:85] offset:1024 nt
	global_load_dwordx4 v[88:91], v23, s[84:85] offset:2048 nt
	global_load_dwordx4 v[92:95], v23, s[84:85] offset:3072 nt
	global_load_dwordx4 v[96:99], v22, s[88:89] nt
	global_load_dwordx4 v[100:103], v22, s[88:89] offset:1024 nt
	global_load_dwordx4 v[104:107], v22, s[88:89] offset:2048 nt
	global_load_dwordx4 v[108:111], v22, s[88:89] offset:3072 nt
	global_load_dwordx4 v[112:115], v23, s[88:89] nt
	global_load_dwordx4 v[116:119], v23, s[88:89] offset:1024 nt
	global_load_dwordx4 v[120:123], v23, s[88:89] offset:2048 nt
	global_load_dwordx4 v[124:127], v23, s[88:89] offset:3072 nt
	s_waitcnt vmcnt(15)
	global_store_dwordx4 v22, v[64:67], s[86:87] nt
	s_waitcnt vmcnt(15)
	global_store_dwordx4 v22, v[68:71], s[86:87] offset:1024 nt
	s_waitcnt vmcnt(15)
	global_store_dwordx4 v22, v[72:75], s[86:87] offset:2048 nt
	s_waitcnt vmcnt(15)
	global_store_dwordx4 v22, v[76:79], s[86:87] offset:3072 nt
	s_waitcnt vmcnt(15)
	global_store_dwordx4 v23, v[80:83], s[86:87] nt
	s_waitcnt vmcnt(15)
	global_store_dwordx4 v23, v[84:87], s[86:87] offset:1024 nt
	s_waitcnt vmcnt(15)
	global_store_dwordx4 v23, v[88:91], s[86:87] offset:2048 nt
	s_waitcnt vmcnt(15)
	global_store_dwordx4 v23, v[92:95], s[86:87] offset:3072 nt
	s_waitcnt vmcnt(15)
	global_store_dwordx4 v22, v[96:99], s[90:91] nt
	s_waitcnt vmcnt(15)
	global_store_dwordx4 v22, v[100:103], s[90:91] offset:1024 nt
	s_waitcnt vmcnt(15)
	global_store_dwordx4 v22, v[104:107], s[90:91] offset:2048 nt
	s_waitcnt vmcnt(15)
	global_store_dwordx4 v22, v[108:111], s[90:91] offset:3072 nt
	s_waitcnt vmcnt(15)
	global_store_dwordx4 v23, v[112:115], s[90:91] nt
	s_waitcnt vmcnt(15)
	global_store_dwordx4 v23, v[116:119], s[90:91] offset:1024 nt
	s_waitcnt vmcnt(15)
	global_store_dwordx4 v23, v[120:123], s[90:91] offset:2048 nt
	s_waitcnt vmcnt(15)
	global_store_dwordx4 v23, v[124:127], s[90:91] offset:3072 nt
	s_add_i32 s80, s101, s100
	s_branch .Lcpy2p_loop
.Lcpy2p_tail:
	s_cmp_lt_u32 s80, 0x7984
	s_cbranch_scc0 .Lcpy2p_end
	s_mul_hi_u32 s81, s80, 0x2ad5802b
	s_lshr_b32 s81, s81, 8
	s_mul_i32 s82, s81, 0x5fa
	s_sub_i32 s82, s80, s82
	s_lshl_b32 s82, s82, 13
	s_and_b32 s83, s81, 31
	s_mul_i32 s83, s83, 0xc00000
	s_add_i32 s82, s82, s83
	s_cmp_lt_u32 s81, 32
	s_cselect_b32 s84, s92, s94
	s_cselect_b32 s85, s93, s95
	s_mov_b32 s83, 0x1f210000
	s_cselect_b32 s83, 0x7210000, s83
	s_add_u32 s84, s84, s82
	s_addc_u32 s85, s85, 0
	s_add_u32 s84, s84, 0xc000
	s_addc_u32 s85, s85, 0
	s_add_u32 s83, s83, s82
	s_add_u32 s86, s98, s83
	s_addc_u32 s87, s99, 0
	global_load_dwordx4 v[64:67], v22, s[84:85] nt
	global_load_dwordx4 v[68:71], v22, s[84:85] offset:1024 nt
	global_load_dwordx4 v[72:75], v22, s[84:85] offset:2048 nt
	global_load_dwordx4 v[76:79], v22, s[84:85] offset:3072 nt
	global_load_dwordx4 v[80:83], v23, s[84:85] nt
	global_load_dwordx4 v[84:87], v23, s[84:85] offset:1024 nt
	global_load_dwordx4 v[88:91], v23, s[84:85] offset:2048 nt
	global_load_dwordx4 v[92:95], v23, s[84:85] offset:3072 nt
	s_waitcnt vmcnt(7)
	global_store_dwordx4 v22, v[64:67], s[86:87] nt
	s_waitcnt vmcnt(7)
	global_store_dwordx4 v22, v[68:71], s[86:87] offset:1024 nt
	s_waitcnt vmcnt(7)
	global_store_dwordx4 v22, v[72:75], s[86:87] offset:2048 nt
	s_waitcnt vmcnt(7)
	global_store_dwordx4 v22, v[76:79], s[86:87] offset:3072 nt
	s_waitcnt vmcnt(7)
	global_store_dwordx4 v23, v[80:83], s[86:87] nt
	s_waitcnt vmcnt(7)
	global_store_dwordx4 v23, v[84:87], s[86:87] offset:1024 nt
	s_waitcnt vmcnt(7)
	global_store_dwordx4 v23, v[88:91], s[86:87] offset:2048 nt
	s_waitcnt vmcnt(7)
	global_store_dwordx4 v23, v[92:95], s[86:87] offset:3072 nt

.Lmg2_end:
	v_lshrrev_b32_e32 v21, 6, v174
	v_and_b32_e32 v22, 63, v174
	v_lshlrev_b32_e32 v22, 4, v22
	v_readfirstlane_b32 s80, v21
	v_add_u32_e32 v23, 0x1000, v22
	v_readfirstlane_b32 s92, v235
	v_readfirstlane_b32 s93, v236
	v_readfirstlane_b32 s94, v237
	v_readfirstlane_b32 s95, v238
	v_readfirstlane_b32 s98, v239
	v_readfirstlane_b32 s99, v240
	s_lshr_b32 s100, s33, 7
	s_lshl_b32 s100, s100, 3
	s_lshr_b32 s101, s33, 3
	s_and_b32 s101, s101, 7
	s_add_i32 s100, s100, s101
	s_lshl_b32 s100, s100, 3
	s_add_i32 s80, s80, s100
	s_add_i32 s80, s80, 0x7984
	s_movk_i32 s100, 0x400

.LBB0_960:
	s_cmp_lt_u32 s33, 96
	s_cbranch_scc1 .Lcpyd_end
	s_cmp_ge_u32 s33, 848
	s_cbranch_scc1 .Lcpyd_end
	v_lshrrev_b32_e32 v21, 6, v174
	v_and_b32_e32 v22, 63, v174
	v_lshlrev_b32_e32 v22, 4, v22
	v_readfirstlane_b32 s80, v21
	v_add_u32_e32 v23, 0x1000, v22
	v_readfirstlane_b32 s92, v235
	v_readfirstlane_b32 s93, v236
	v_readfirstlane_b32 s94, v237
	v_readfirstlane_b32 s95, v238
	v_readfirstlane_b32 s98, v239
	v_readfirstlane_b32 s99, v240
	s_add_i32 s80, s80, s33
	s_add_i32 s80, s80, 0x7ae0
	s_movk_i32 s100, 752
.Lcpyd_loop:
	s_add_i32 s101, s80, s100
	s_cmp_lt_u32 s101, 0x9698
	s_cbranch_scc0 .Lcpyd_tail
	s_mul_hi_u32 s81, s80, 0x2ad5802b
	s_lshr_b32 s81, s81, 8
	s_mul_i32 s82, s81, 0x5fa
	s_sub_i32 s82, s80, s82
	s_lshl_b32 s82, s82, 13
	s_and_b32 s83, s81, 31
	s_mul_i32 s83, s83, 0xc00000
	s_add_i32 s82, s82, s83
	s_cmp_lt_u32 s81, 32
	s_cselect_b32 s84, s92, s94
	s_cselect_b32 s85, s93, s95
	s_mov_b32 s83, 0x1f210000
	s_cselect_b32 s83, 0x7210000, s83
	s_add_u32 s84, s84, s82
	s_addc_u32 s85, s85, 0
	s_add_u32 s84, s84, 0xc000
	s_addc_u32 s85, s85, 0
	s_add_u32 s83, s83, s82
	s_add_u32 s86, s98, s83
	s_addc_u32 s87, s99, 0
	s_mul_hi_u32 s81, s101, 0x2ad5802b
	s_lshr_b32 s81, s81, 8
	s_mul_i32 s82, s81, 0x5fa
	s_sub_i32 s82, s101, s82
	s_lshl_b32 s82, s82, 13
	s_and_b32 s83, s81, 31
	s_mul_i32 s83, s83, 0xc00000
	s_add_i32 s82, s82, s83
	s_cmp_lt_u32 s81, 32
	s_cselect_b32 s88, s92, s94
	s_cselect_b32 s89, s93, s95
	s_mov_b32 s83, 0x1f210000
	s_cselect_b32 s83, 0x7210000, s83
	s_add_u32 s88, s88, s82
	s_addc_u32 s89, s89, 0
	s_add_u32 s88, s88, 0xc000
	s_addc_u32 s89, s89, 0
	s_add_u32 s83, s83, s82
	s_add_u32 s90, s98, s83
	s_addc_u32 s91, s99, 0
	global_load_dwordx4 v[64:67], v22, s[84:85] nt
	global_load_dwordx4 v[68:71], v22, s[84:85] offset:1024 nt
	global_load_dwordx4 v[72:75], v22, s[84:85] offset:2048 nt
	global_load_dwordx4 v[76:79], v22, s[84:85] offset:3072 nt
	global_load_dwordx4 v[80:83], v23, s[84:85] nt
	global_load_dwordx4 v[84:87], v23, s[84:85] offset:1024 nt
	global_load_dwordx4 v[88:91], v23, s[84:85] offset:2048 nt
	global_load_dwordx4 v[92:95], v23, s[84:85] offset:3072 nt
	global_load_dwordx4 v[96:99], v22, s[88:89] nt
	global_load_dwordx4 v[100:103], v22, s[88:89] offset:1024 nt
	global_load_dwordx4 v[104:107], v22, s[88:89] offset:2048 nt
	global_load_dwordx4 v[108:111], v22, s[88:89] offset:3072 nt
	global_load_dwordx4 v[112:115], v23, s[88:89] nt
	global_load_dwordx4 v[116:119], v23, s[88:89] offset:1024 nt
	global_load_dwordx4 v[120:123], v23, s[88:89] offset:2048 nt
	global_load_dwordx4 v[124:127], v23, s[88:89] offset:3072 nt
	s_waitcnt vmcnt(15)
	global_store_dwordx4 v22, v[64:67], s[86:87] nt
	s_waitcnt vmcnt(15)
	global_store_dwordx4 v22, v[68:71], s[86:87] offset:1024 nt
	s_waitcnt vmcnt(15)
	global_store_dwordx4 v22, v[72:75], s[86:87] offset:2048 nt
	s_waitcnt vmcnt(15)
	global_store_dwordx4 v22, v[76:79], s[86:87] offset:3072 nt
	s_waitcnt vmcnt(15)
	global_store_dwordx4 v23, v[80:83], s[86:87] nt
	s_waitcnt vmcnt(15)
	global_store_dwordx4 v23, v[84:87], s[86:87] offset:1024 nt
	s_waitcnt vmcnt(15)
	global_store_dwordx4 v23, v[88:91], s[86:87] offset:2048 nt
	s_waitcnt vmcnt(15)
	global_store_dwordx4 v23, v[92:95], s[86:87] offset:3072 nt
	s_waitcnt vmcnt(15)
	global_store_dwordx4 v22, v[96:99], s[90:91] nt
	s_waitcnt vmcnt(15)
	global_store_dwordx4 v22, v[100:103], s[90:91] offset:1024 nt
	s_waitcnt vmcnt(15)
	global_store_dwordx4 v22, v[104:107], s[90:91] offset:2048 nt
	s_waitcnt vmcnt(15)
	global_store_dwordx4 v22, v[108:111], s[90:91] offset:3072 nt
	s_waitcnt vmcnt(15)
	global_store_dwordx4 v23, v[112:115], s[90:91] nt
	s_waitcnt vmcnt(15)
	global_store_dwordx4 v23, v[116:119], s[90:91] offset:1024 nt
	s_waitcnt vmcnt(15)
	global_store_dwordx4 v23, v[120:123], s[90:91] offset:2048 nt
	s_waitcnt vmcnt(15)
	global_store_dwordx4 v23, v[124:127], s[90:91] offset:3072 nt
	s_add_i32 s80, s101, s100
	s_branch .Lcpyd_loop
.Lcpyd_tail:
	s_cmp_lt_u32 s80, 0x9698
	s_cbranch_scc0 .Lcpyd_end
	s_mul_hi_u32 s81, s80, 0x2ad5802b
	s_lshr_b32 s81, s81, 8
	s_mul_i32 s82, s81, 0x5fa
	s_sub_i32 s82, s80, s82
	s_lshl_b32 s82, s82, 13
	s_and_b32 s83, s81, 31
	s_mul_i32 s83, s83, 0xc00000
	s_add_i32 s82, s82, s83
	s_cmp_lt_u32 s81, 32
	s_cselect_b32 s84, s92, s94
	s_cselect_b32 s85, s93, s95
	s_mov_b32 s83, 0x1f210000
	s_cselect_b32 s83, 0x7210000, s83
	s_add_u32 s84, s84, s82
	s_addc_u32 s85, s85, 0
	s_add_u32 s84, s84, 0xc000
	s_addc_u32 s85, s85, 0
	s_add_u32 s83, s83, s82
	s_add_u32 s86, s98, s83
	s_addc_u32 s87, s99, 0
	global_load_dwordx4 v[64:67], v22, s[84:85] nt
	global_load_dwordx4 v[68:71], v22, s[84:85] offset:1024 nt
	global_load_dwordx4 v[72:75], v22, s[84:85] offset:2048 nt
	global_load_dwordx4 v[76:79], v22, s[84:85] offset:3072 nt
	global_load_dwordx4 v[80:83], v23, s[84:85] nt
	global_load_dwordx4 v[84:87], v23, s[84:85] offset:1024 nt
	global_load_dwordx4 v[88:91], v23, s[84:85] offset:2048 nt
	global_load_dwordx4 v[92:95], v23, s[84:85] offset:3072 nt
	s_waitcnt vmcnt(7)
	global_store_dwordx4 v22, v[64:67], s[86:87] nt
	s_waitcnt vmcnt(7)
	global_store_dwordx4 v22, v[68:71], s[86:87] offset:1024 nt
	s_waitcnt vmcnt(7)
	global_store_dwordx4 v22, v[72:75], s[86:87] offset:2048 nt
	s_waitcnt vmcnt(7)
	global_store_dwordx4 v22, v[76:79], s[86:87] offset:3072 nt
	s_waitcnt vmcnt(7)
	global_store_dwordx4 v23, v[80:83], s[86:87] nt
	s_waitcnt vmcnt(7)
	global_store_dwordx4 v23, v[84:87], s[86:87] offset:1024 nt
	s_waitcnt vmcnt(7)
	global_store_dwordx4 v23, v[88:91], s[86:87] offset:2048 nt
	s_waitcnt vmcnt(7)
	global_store_dwordx4 v23, v[92:95], s[86:87] offset:3072 nt

.LBB0_980:
	s_or_b64 exec, exec, s[8:9]
	v_readlane_b32 s4, v234, 2
	v_mov_b32_e32 v8, v174
	v_readlane_b32 s5, v234, 3
	s_barrier
	s_and_b32 s80, s33, 64
	s_cmp_eq_u32 s80, 0
	s_cbranch_scc1 .Lpre3_skip
	v_lshrrev_b32_e32 v21, 6, v174
	v_and_b32_e32 v22, 63, v174
	v_lshlrev_b32_e32 v22, 4, v22
	v_readfirstlane_b32 s80, v21
	v_add_u32_e32 v23, 0x1000, v22
	v_readfirstlane_b32 s92, v235
	v_readfirstlane_b32 s93, v236
	v_readfirstlane_b32 s94, v237
	v_readfirstlane_b32 s95, v238
	v_readfirstlane_b32 s98, v239
	v_readfirstlane_b32 s99, v240
	s_lshr_b32 s100, s33, 7
	s_lshl_b32 s100, s100, 3
	s_lshr_b32 s101, s33, 3
	s_and_b32 s101, s101, 7
	s_add_i32 s100, s100, s101
	s_lshl_b32 s100, s100, 3
	s_add_i32 s80, s80, s100
	s_add_i32 s80, s80, 0x9698
	s_movk_i32 s100, 0x400
.Lcpy3p_loop:
	s_add_i32 s101, s80, s100
	s_cmp_lt_u32 s101, 0x9bcc
	s_cbranch_scc0 .Lcpy3p_tail
	s_mul_hi_u32 s81, s80, 0x2ad5802b
	s_lshr_b32 s81, s81, 8
	s_mul_i32 s82, s81, 0x5fa
	s_sub_i32 s82, s80, s82
	s_lshl_b32 s82, s82, 13
	s_and_b32 s83, s81, 31
	s_mul_i32 s83, s83, 0xc00000
	s_add_i32 s82, s82, s83
	s_cmp_lt_u32 s81, 32
	s_cselect_b32 s84, s92, s94
	s_cselect_b32 s85, s93, s95
	s_mov_b32 s83, 0x1f210000
	s_cselect_b32 s83, 0x7210000, s83
	s_add_u32 s84, s84, s82
	s_addc_u32 s85, s85, 0
	s_add_u32 s84, s84, 0xc000
	s_addc_u32 s85, s85, 0
	s_add_u32 s83, s83, s82
	s_add_u32 s86, s98, s83
	s_addc_u32 s87, s99, 0
	s_mul_hi_u32 s81, s101, 0x2ad5802b
	s_lshr_b32 s81, s81, 8
	s_mul_i32 s82, s81, 0x5fa
	s_sub_i32 s82, s101, s82
	s_lshl_b32 s82, s82, 13
	s_and_b32 s83, s81, 31
	s_mul_i32 s83, s83, 0xc00000
	s_add_i32 s82, s82, s83
	s_cmp_lt_u32 s81, 32
	s_cselect_b32 s88, s92, s94
	s_cselect_b32 s89, s93, s95
	s_mov_b32 s83, 0x1f210000
	s_cselect_b32 s83, 0x7210000, s83
	s_add_u32 s88, s88, s82
	s_addc_u32 s89, s89, 0
	s_add_u32 s88, s88, 0xc000
	s_addc_u32 s89, s89, 0
	s_add_u32 s83, s83, s82
	s_add_u32 s90, s98, s83
	s_addc_u32 s91, s99, 0
	global_load_dwordx4 v[64:67], v22, s[84:85] nt
	global_load_dwordx4 v[68:71], v22, s[84:85] offset:1024 nt
	global_load_dwordx4 v[72:75], v22, s[84:85] offset:2048 nt
	global_load_dwordx4 v[76:79], v22, s[84:85] offset:3072 nt
	global_load_dwordx4 v[80:83], v23, s[84:85] nt
	global_load_dwordx4 v[84:87], v23, s[84:85] offset:1024 nt
	global_load_dwordx4 v[88:91], v23, s[84:85] offset:2048 nt
	global_load_dwordx4 v[92:95], v23, s[84:85] offset:3072 nt
	global_load_dwordx4 v[96:99], v22, s[88:89] nt
	global_load_dwordx4 v[100:103], v22, s[88:89] offset:1024 nt
	global_load_dwordx4 v[104:107], v22, s[88:89] offset:2048 nt
	global_load_dwordx4 v[108:111], v22, s[88:89] offset:3072 nt
	global_load_dwordx4 v[112:115], v23, s[88:89] nt
	global_load_dwordx4 v[116:119], v23, s[88:89] offset:1024 nt
	global_load_dwordx4 v[120:123], v23, s[88:89] offset:2048 nt
	global_load_dwordx4 v[124:127], v23, s[88:89] offset:3072 nt
	s_waitcnt vmcnt(15)
	global_store_dwordx4 v22, v[64:67], s[86:87] nt
	s_waitcnt vmcnt(15)
	global_store_dwordx4 v22, v[68:71], s[86:87] offset:1024 nt
	s_waitcnt vmcnt(15)
	global_store_dwordx4 v22, v[72:75], s[86:87] offset:2048 nt
	s_waitcnt vmcnt(15)
	global_store_dwordx4 v22, v[76:79], s[86:87] offset:3072 nt
	s_waitcnt vmcnt(15)
	global_store_dwordx4 v23, v[80:83], s[86:87] nt
	s_waitcnt vmcnt(15)
	global_store_dwordx4 v23, v[84:87], s[86:87] offset:1024 nt
	s_waitcnt vmcnt(15)
	global_store_dwordx4 v23, v[88:91], s[86:87] offset:2048 nt
	s_waitcnt vmcnt(15)
	global_store_dwordx4 v23, v[92:95], s[86:87] offset:3072 nt
	s_waitcnt vmcnt(15)
	global_store_dwordx4 v22, v[96:99], s[90:91] nt
	s_waitcnt vmcnt(15)
	global_store_dwordx4 v22, v[100:103], s[90:91] offset:1024 nt
	s_waitcnt vmcnt(15)
	global_store_dwordx4 v22, v[104:107], s[90:91] offset:2048 nt
	s_waitcnt vmcnt(15)
	global_store_dwordx4 v22, v[108:111], s[90:91] offset:3072 nt
	s_waitcnt vmcnt(15)
	global_store_dwordx4 v23, v[112:115], s[90:91] nt
	s_waitcnt vmcnt(15)
	global_store_dwordx4 v23, v[116:119], s[90:91] offset:1024 nt
	s_waitcnt vmcnt(15)
	global_store_dwordx4 v23, v[120:123], s[90:91] offset:2048 nt
	s_waitcnt vmcnt(15)
	global_store_dwordx4 v23, v[124:127], s[90:91] offset:3072 nt
	s_add_i32 s80, s101, s100
	s_branch .Lcpy3p_loop
.Lcpy3p_tail:
	s_cmp_lt_u32 s80, 0x9bcc
	s_cbranch_scc0 .Lcpy3p_end
	s_mul_hi_u32 s81, s80, 0x2ad5802b
	s_lshr_b32 s81, s81, 8
	s_mul_i32 s82, s81, 0x5fa
	s_sub_i32 s82, s80, s82
	s_lshl_b32 s82, s82, 13
	s_and_b32 s83, s81, 31
	s_mul_i32 s83, s83, 0xc00000
	s_add_i32 s82, s82, s83
	s_cmp_lt_u32 s81, 32
	s_cselect_b32 s84, s92, s94
	s_cselect_b32 s85, s93, s95
	s_mov_b32 s83, 0x1f210000
	s_cselect_b32 s83, 0x7210000, s83
	s_add_u32 s84, s84, s82
	s_addc_u32 s85, s85, 0
	s_add_u32 s84, s84, 0xc000
	s_addc_u32 s85, s85, 0
	s_add_u32 s83, s83, s82
	s_add_u32 s86, s98, s83
	s_addc_u32 s87, s99, 0
	global_load_dwordx4 v[64:67], v22, s[84:85] nt
	global_load_dwordx4 v[68:71], v22, s[84:85] offset:1024 nt
	global_load_dwordx4 v[72:75], v22, s[84:85] offset:2048 nt
	global_load_dwordx4 v[76:79], v22, s[84:85] offset:3072 nt
	global_load_dwordx4 v[80:83], v23, s[84:85] nt
	global_load_dwordx4 v[84:87], v23, s[84:85] offset:1024 nt
	global_load_dwordx4 v[88:91], v23, s[84:85] offset:2048 nt
	global_load_dwordx4 v[92:95], v23, s[84:85] offset:3072 nt
	s_waitcnt vmcnt(7)
	global_store_dwordx4 v22, v[64:67], s[86:87] nt
	s_waitcnt vmcnt(7)
	global_store_dwordx4 v22, v[68:71], s[86:87] offset:1024 nt
	s_waitcnt vmcnt(7)
	global_store_dwordx4 v22, v[72:75], s[86:87] offset:2048 nt
	s_waitcnt vmcnt(7)
	global_store_dwordx4 v22, v[76:79], s[86:87] offset:3072 nt
	s_waitcnt vmcnt(7)
	global_store_dwordx4 v23, v[80:83], s[86:87] nt
	s_waitcnt vmcnt(7)
	global_store_dwordx4 v23, v[84:87], s[86:87] offset:1024 nt
	s_waitcnt vmcnt(7)
	global_store_dwordx4 v23, v[88:91], s[86:87] offset:2048 nt
	s_waitcnt vmcnt(7)
	global_store_dwordx4 v23, v[92:95], s[86:87] offset:3072 nt

.Lmg3_end:
	v_lshrrev_b32_e32 v21, 6, v174
	v_and_b32_e32 v22, 63, v174
	v_lshlrev_b32_e32 v22, 4, v22
	v_readfirstlane_b32 s80, v21
	v_add_u32_e32 v23, 0x1000, v22
	v_readfirstlane_b32 s92, v235
	v_readfirstlane_b32 s93, v236
	v_readfirstlane_b32 s94, v237
	v_readfirstlane_b32 s95, v238
	v_readfirstlane_b32 s98, v239
	v_readfirstlane_b32 s99, v240
	s_lshr_b32 s100, s33, 7
	s_lshl_b32 s100, s100, 3
	s_lshr_b32 s101, s33, 3
	s_and_b32 s101, s101, 7
	s_add_i32 s100, s100, s101
	s_lshl_b32 s100, s100, 3
	s_add_i32 s80, s80, s100
	s_add_i32 s80, s80, 0x9bcc
	s_movk_i32 s100, 0x400
.Lcpy3_loop:
	s_add_i32 s101, s80, s100
	s_cmp_lt_u32 s101, 0x9d88
	s_cbranch_scc0 .Lcpy3_tail
	s_mul_hi_u32 s81, s80, 0x2ad5802b
	s_lshr_b32 s81, s81, 8
	s_mul_i32 s82, s81, 0x5fa
	s_sub_i32 s82, s80, s82
	s_lshl_b32 s82, s82, 13
	s_and_b32 s83, s81, 31
	s_mul_i32 s83, s83, 0xc00000
	s_add_i32 s82, s82, s83
	s_cmp_lt_u32 s81, 32
	s_cselect_b32 s84, s92, s94
	s_cselect_b32 s85, s93, s95
	s_mov_b32 s83, 0x1f210000
	s_cselect_b32 s83, 0x7210000, s83
	s_add_u32 s84, s84, s82
	s_addc_u32 s85, s85, 0
	s_add_u32 s84, s84, 0xc000
	s_addc_u32 s85, s85, 0
	s_add_u32 s83, s83, s82
	s_add_u32 s86, s98, s83
	s_addc_u32 s87, s99, 0
	s_mul_hi_u32 s81, s101, 0x2ad5802b
	s_lshr_b32 s81, s81, 8
	s_mul_i32 s82, s81, 0x5fa
	s_sub_i32 s82, s101, s82
	s_lshl_b32 s82, s82, 13
	s_and_b32 s83, s81, 31
	s_mul_i32 s83, s83, 0xc00000
	s_add_i32 s82, s82, s83
	s_cmp_lt_u32 s81, 32
	s_cselect_b32 s88, s92, s94
	s_cselect_b32 s89, s93, s95
	s_mov_b32 s83, 0x1f210000
	s_cselect_b32 s83, 0x7210000, s83
	s_add_u32 s88, s88, s82
	s_addc_u32 s89, s89, 0
	s_add_u32 s88, s88, 0xc000
	s_addc_u32 s89, s89, 0
	s_add_u32 s83, s83, s82
	s_add_u32 s90, s98, s83
	s_addc_u32 s91, s99, 0
	global_load_dwordx4 v[64:67], v22, s[84:85] nt
	global_load_dwordx4 v[68:71], v22, s[84:85] offset:1024 nt
	global_load_dwordx4 v[72:75], v22, s[84:85] offset:2048 nt
	global_load_dwordx4 v[76:79], v22, s[84:85] offset:3072 nt
	global_load_dwordx4 v[80:83], v23, s[84:85] nt
	global_load_dwordx4 v[84:87], v23, s[84:85] offset:1024 nt
	global_load_dwordx4 v[88:91], v23, s[84:85] offset:2048 nt
	global_load_dwordx4 v[92:95], v23, s[84:85] offset:3072 nt
	global_load_dwordx4 v[96:99], v22, s[88:89] nt
	global_load_dwordx4 v[100:103], v22, s[88:89] offset:1024 nt
	global_load_dwordx4 v[104:107], v22, s[88:89] offset:2048 nt
	global_load_dwordx4 v[108:111], v22, s[88:89] offset:3072 nt
	global_load_dwordx4 v[112:115], v23, s[88:89] nt
	global_load_dwordx4 v[116:119], v23, s[88:89] offset:1024 nt
	global_load_dwordx4 v[120:123], v23, s[88:89] offset:2048 nt
	global_load_dwordx4 v[124:127], v23, s[88:89] offset:3072 nt
	s_waitcnt vmcnt(15)
	global_store_dwordx4 v22, v[64:67], s[86:87] nt
	s_waitcnt vmcnt(15)
	global_store_dwordx4 v22, v[68:71], s[86:87] offset:1024 nt
	s_waitcnt vmcnt(15)
	global_store_dwordx4 v22, v[72:75], s[86:87] offset:2048 nt
	s_waitcnt vmcnt(15)
	global_store_dwordx4 v22, v[76:79], s[86:87] offset:3072 nt
	s_waitcnt vmcnt(15)
	global_store_dwordx4 v23, v[80:83], s[86:87] nt
	s_waitcnt vmcnt(15)
	global_store_dwordx4 v23, v[84:87], s[86:87] offset:1024 nt
	s_waitcnt vmcnt(15)
	global_store_dwordx4 v23, v[88:91], s[86:87] offset:2048 nt
	s_waitcnt vmcnt(15)
	global_store_dwordx4 v23, v[92:95], s[86:87] offset:3072 nt
	s_waitcnt vmcnt(15)
	global_store_dwordx4 v22, v[96:99], s[90:91] nt
	s_waitcnt vmcnt(15)
	global_store_dwordx4 v22, v[100:103], s[90:91] offset:1024 nt
	s_waitcnt vmcnt(15)
	global_store_dwordx4 v22, v[104:107], s[90:91] offset:2048 nt
	s_waitcnt vmcnt(15)
	global_store_dwordx4 v22, v[108:111], s[90:91] offset:3072 nt
	s_waitcnt vmcnt(15)
	global_store_dwordx4 v23, v[112:115], s[90:91] nt
	s_waitcnt vmcnt(15)
	global_store_dwordx4 v23, v[116:119], s[90:91] offset:1024 nt
	s_waitcnt vmcnt(15)
	global_store_dwordx4 v23, v[120:123], s[90:91] offset:2048 nt
	s_waitcnt vmcnt(15)
	global_store_dwordx4 v23, v[124:127], s[90:91] offset:3072 nt
	s_add_i32 s80, s101, s100
	s_branch .Lcpy3_loop
.Lcpy3_tail:
	s_cmp_lt_u32 s80, 0x9d88
	s_cbranch_scc0 .Lcpy3_end
	s_mul_hi_u32 s81, s80, 0x2ad5802b
	s_lshr_b32 s81, s81, 8
	s_mul_i32 s82, s81, 0x5fa
	s_sub_i32 s82, s80, s82
	s_lshl_b32 s82, s82, 13
	s_and_b32 s83, s81, 31
	s_mul_i32 s83, s83, 0xc00000
	s_add_i32 s82, s82, s83
	s_cmp_lt_u32 s81, 32
	s_cselect_b32 s84, s92, s94
	s_cselect_b32 s85, s93, s95
	s_mov_b32 s83, 0x1f210000
	s_cselect_b32 s83, 0x7210000, s83
	s_add_u32 s84, s84, s82
	s_addc_u32 s85, s85, 0
	s_add_u32 s84, s84, 0xc000
	s_addc_u32 s85, s85, 0
	s_add_u32 s83, s83, s82
	s_add_u32 s86, s98, s83
	s_addc_u32 s87, s99, 0
	global_load_dwordx4 v[64:67], v22, s[84:85] nt
	global_load_dwordx4 v[68:71], v22, s[84:85] offset:1024 nt
	global_load_dwordx4 v[72:75], v22, s[84:85] offset:2048 nt
	global_load_dwordx4 v[76:79], v22, s[84:85] offset:3072 nt
	global_load_dwordx4 v[80:83], v23, s[84:85] nt
	global_load_dwordx4 v[84:87], v23, s[84:85] offset:1024 nt
	global_load_dwordx4 v[88:91], v23, s[84:85] offset:2048 nt
	global_load_dwordx4 v[92:95], v23, s[84:85] offset:3072 nt
	s_waitcnt vmcnt(7)
	global_store_dwordx4 v22, v[64:67], s[86:87] nt
	s_waitcnt vmcnt(7)
	global_store_dwordx4 v22, v[68:71], s[86:87] offset:1024 nt
	s_waitcnt vmcnt(7)
	global_store_dwordx4 v22, v[72:75], s[86:87] offset:2048 nt
	s_waitcnt vmcnt(7)
	global_store_dwordx4 v22, v[76:79], s[86:87] offset:3072 nt
	s_waitcnt vmcnt(7)
	global_store_dwordx4 v23, v[80:83], s[86:87] nt
	s_waitcnt vmcnt(7)
	global_store_dwordx4 v23, v[84:87], s[86:87] offset:1024 nt
	s_waitcnt vmcnt(7)
	global_store_dwordx4 v23, v[88:91], s[86:87] offset:2048 nt
	s_waitcnt vmcnt(7)
	global_store_dwordx4 v23, v[92:95], s[86:87] offset:3072 nt

.LBB0_1288:
	s_cmp_lt_u32 s33, 1072
	s_cbranch_scc1 .Lcpye_end
	v_lshrrev_b32_e32 v21, 6, v174
	v_and_b32_e32 v22, 63, v174
	v_lshlrev_b32_e32 v22, 4, v22
	v_readfirstlane_b32 s80, v21
	v_add_u32_e32 v23, 0x1000, v22
	v_readfirstlane_b32 s92, v235
	v_readfirstlane_b32 s93, v236
	v_readfirstlane_b32 s94, v237
	v_readfirstlane_b32 s95, v238
	v_readfirstlane_b32 s98, v239
	v_readfirstlane_b32 s99, v240
	s_add_i32 s80, s80, s33
	s_add_i32 s80, s80, 0x9958
	s_sub_i32 s100, s78, 134
	s_lshl_b32 s100, s100, 3
.Lcpye_loop:
	s_add_i32 s101, s80, s100
	s_cmp_lt_u32 s101, 0xbcc8
	s_cbranch_scc0 .Lcpye_tail
	s_mul_hi_u32 s81, s80, 0x2ad5802b
	s_lshr_b32 s81, s81, 8
	s_mul_i32 s82, s81, 0x5fa
	s_sub_i32 s82, s80, s82
	s_lshl_b32 s82, s82, 13
	s_and_b32 s83, s81, 31
	s_mul_i32 s83, s83, 0xc00000
	s_add_i32 s82, s82, s83
	s_cmp_lt_u32 s81, 32
	s_cselect_b32 s84, s92, s94
	s_cselect_b32 s85, s93, s95
	s_mov_b32 s83, 0x1f210000
	s_cselect_b32 s83, 0x7210000, s83
	s_add_u32 s84, s84, s82
	s_addc_u32 s85, s85, 0
	s_add_u32 s84, s84, 0xc000
	s_addc_u32 s85, s85, 0
	s_add_u32 s83, s83, s82
	s_add_u32 s86, s98, s83
	s_addc_u32 s87, s99, 0
	s_mul_hi_u32 s81, s101, 0x2ad5802b
	s_lshr_b32 s81, s81, 8
	s_mul_i32 s82, s81, 0x5fa
	s_sub_i32 s82, s101, s82
	s_lshl_b32 s82, s82, 13
	s_and_b32 s83, s81, 31
	s_mul_i32 s83, s83, 0xc00000
	s_add_i32 s82, s82, s83
	s_cmp_lt_u32 s81, 32
	s_cselect_b32 s88, s92, s94
	s_cselect_b32 s89, s93, s95
	s_mov_b32 s83, 0x1f210000
	s_cselect_b32 s83, 0x7210000, s83
	s_add_u32 s88, s88, s82
	s_addc_u32 s89, s89, 0
	s_add_u32 s88, s88, 0xc000
	s_addc_u32 s89, s89, 0
	s_add_u32 s83, s83, s82
	s_add_u32 s90, s98, s83
	s_addc_u32 s91, s99, 0
	global_load_dwordx4 v[64:67], v22, s[84:85] nt
	global_load_dwordx4 v[68:71], v22, s[84:85] offset:1024 nt
	global_load_dwordx4 v[72:75], v22, s[84:85] offset:2048 nt
	global_load_dwordx4 v[76:79], v22, s[84:85] offset:3072 nt
	global_load_dwordx4 v[80:83], v23, s[84:85] nt
	global_load_dwordx4 v[84:87], v23, s[84:85] offset:1024 nt
	global_load_dwordx4 v[88:91], v23, s[84:85] offset:2048 nt
	global_load_dwordx4 v[92:95], v23, s[84:85] offset:3072 nt
	global_load_dwordx4 v[96:99], v22, s[88:89] nt
	global_load_dwordx4 v[100:103], v22, s[88:89] offset:1024 nt
	global_load_dwordx4 v[104:107], v22, s[88:89] offset:2048 nt
	global_load_dwordx4 v[108:111], v22, s[88:89] offset:3072 nt
	global_load_dwordx4 v[112:115], v23, s[88:89] nt
	global_load_dwordx4 v[116:119], v23, s[88:89] offset:1024 nt
	global_load_dwordx4 v[120:123], v23, s[88:89] offset:2048 nt
	global_load_dwordx4 v[124:127], v23, s[88:89] offset:3072 nt
	s_waitcnt vmcnt(15)
	global_store_dwordx4 v22, v[64:67], s[86:87] nt
	s_waitcnt vmcnt(15)
	global_store_dwordx4 v22, v[68:71], s[86:87] offset:1024 nt
	s_waitcnt vmcnt(15)
	global_store_dwordx4 v22, v[72:75], s[86:87] offset:2048 nt
	s_waitcnt vmcnt(15)
	global_store_dwordx4 v22, v[76:79], s[86:87] offset:3072 nt
	s_waitcnt vmcnt(15)
	global_store_dwordx4 v23, v[80:83], s[86:87] nt
	s_waitcnt vmcnt(15)
	global_store_dwordx4 v23, v[84:87], s[86:87] offset:1024 nt
	s_waitcnt vmcnt(15)
	global_store_dwordx4 v23, v[88:91], s[86:87] offset:2048 nt
	s_waitcnt vmcnt(15)
	global_store_dwordx4 v23, v[92:95], s[86:87] offset:3072 nt
	s_waitcnt vmcnt(15)
	global_store_dwordx4 v22, v[96:99], s[90:91] nt
	s_waitcnt vmcnt(15)
	global_store_dwordx4 v22, v[100:103], s[90:91] offset:1024 nt
	s_waitcnt vmcnt(15)
	global_store_dwordx4 v22, v[104:107], s[90:91] offset:2048 nt
	s_waitcnt vmcnt(15)
	global_store_dwordx4 v22, v[108:111], s[90:91] offset:3072 nt
	s_waitcnt vmcnt(15)
	global_store_dwordx4 v23, v[112:115], s[90:91] nt
	s_waitcnt vmcnt(15)
	global_store_dwordx4 v23, v[116:119], s[90:91] offset:1024 nt
	s_waitcnt vmcnt(15)
	global_store_dwordx4 v23, v[120:123], s[90:91] offset:2048 nt
	s_waitcnt vmcnt(15)
	global_store_dwordx4 v23, v[124:127], s[90:91] offset:3072 nt
	s_add_i32 s80, s101, s100
	s_branch .Lcpye_loop
.Lcpye_tail:
	s_cmp_lt_u32 s80, 0xbcc8
	s_cbranch_scc0 .Lcpye_end
	s_mul_hi_u32 s81, s80, 0x2ad5802b
	s_lshr_b32 s81, s81, 8
	s_mul_i32 s82, s81, 0x5fa
	s_sub_i32 s82, s80, s82
	s_lshl_b32 s82, s82, 13
	s_and_b32 s83, s81, 31
	s_mul_i32 s83, s83, 0xc00000
	s_add_i32 s82, s82, s83
	s_cmp_lt_u32 s81, 32
	s_cselect_b32 s84, s92, s94
	s_cselect_b32 s85, s93, s95
	s_mov_b32 s83, 0x1f210000
	s_cselect_b32 s83, 0x7210000, s83
	s_add_u32 s84, s84, s82
	s_addc_u32 s85, s85, 0
	s_add_u32 s84, s84, 0xc000
	s_addc_u32 s85, s85, 0
	s_add_u32 s83, s83, s82
	s_add_u32 s86, s98, s83
	s_addc_u32 s87, s99, 0
	global_load_dwordx4 v[64:67], v22, s[84:85] nt
	global_load_dwordx4 v[68:71], v22, s[84:85] offset:1024 nt
	global_load_dwordx4 v[72:75], v22, s[84:85] offset:2048 nt
	global_load_dwordx4 v[76:79], v22, s[84:85] offset:3072 nt
	global_load_dwordx4 v[80:83], v23, s[84:85] nt
	global_load_dwordx4 v[84:87], v23, s[84:85] offset:1024 nt
	global_load_dwordx4 v[88:91], v23, s[84:85] offset:2048 nt
	global_load_dwordx4 v[92:95], v23, s[84:85] offset:3072 nt
	s_waitcnt vmcnt(7)
	global_store_dwordx4 v22, v[64:67], s[86:87] nt
	s_waitcnt vmcnt(7)
	global_store_dwordx4 v22, v[68:71], s[86:87] offset:1024 nt
	s_waitcnt vmcnt(7)
	global_store_dwordx4 v22, v[72:75], s[86:87] offset:2048 nt
	s_waitcnt vmcnt(7)
	global_store_dwordx4 v22, v[76:79], s[86:87] offset:3072 nt
	s_waitcnt vmcnt(7)
	global_store_dwordx4 v23, v[80:83], s[86:87] nt
	s_waitcnt vmcnt(7)
	global_store_dwordx4 v23, v[84:87], s[86:87] offset:1024 nt
	s_waitcnt vmcnt(7)
	global_store_dwordx4 v23, v[88:91], s[86:87] offset:2048 nt
	s_waitcnt vmcnt(7)
	global_store_dwordx4 v23, v[92:95], s[86:87] offset:3072 nt

.LBB0_1383:
	s_or_b64 exec, exec, s[8:9]
	v_readlane_b32 s4, v234, 2
	v_mov_b32_e32 v8, v174
	v_readlane_b32 s5, v234, 3
	s_barrier
	s_and_b32 s80, s33, 64
	s_cmp_eq_u32 s80, 0
	s_cbranch_scc1 .Lpref_skip
	v_lshrrev_b32_e32 v21, 6, v174
	v_and_b32_e32 v22, 63, v174
	v_lshlrev_b32_e32 v22, 4, v22
	v_readfirstlane_b32 s80, v21
	v_add_u32_e32 v23, 0x1000, v22
	v_readfirstlane_b32 s92, v235
	v_readfirstlane_b32 s93, v236
	v_readfirstlane_b32 s94, v237
	v_readfirstlane_b32 s95, v238
	v_readfirstlane_b32 s98, v239
	v_readfirstlane_b32 s99, v240
	s_lshr_b32 s100, s33, 7
	s_lshl_b32 s100, s100, 3
	s_lshr_b32 s101, s33, 3
	s_and_b32 s101, s101, 7
	s_add_i32 s100, s100, s101
	s_lshl_b32 s100, s100, 3
	s_add_i32 s80, s80, s100
	s_add_i32 s80, s80, 0xbcc8
	s_movk_i32 s100, 0x400
.Lcpyfp_loop:
	s_add_i32 s101, s80, s100
	s_cmp_lt_u32 s101, 0xcb6e
	s_cbranch_scc0 .Lcpyfp_tail
	s_mul_hi_u32 s81, s80, 0x2ad5802b
	s_lshr_b32 s81, s81, 8
	s_mul_i32 s82, s81, 0x5fa
	s_sub_i32 s82, s80, s82
	s_lshl_b32 s82, s82, 13
	s_and_b32 s83, s81, 31
	s_mul_i32 s83, s83, 0xc00000
	s_add_i32 s82, s82, s83
	s_cmp_lt_u32 s81, 32
	s_cselect_b32 s84, s92, s94
	s_cselect_b32 s85, s93, s95
	s_mov_b32 s83, 0x1f210000
	s_cselect_b32 s83, 0x7210000, s83
	s_add_u32 s84, s84, s82
	s_addc_u32 s85, s85, 0
	s_add_u32 s84, s84, 0xc000
	s_addc_u32 s85, s85, 0
	s_add_u32 s83, s83, s82
	s_add_u32 s86, s98, s83
	s_addc_u32 s87, s99, 0
	s_mul_hi_u32 s81, s101, 0x2ad5802b
	s_lshr_b32 s81, s81, 8
	s_mul_i32 s82, s81, 0x5fa
	s_sub_i32 s82, s101, s82
	s_lshl_b32 s82, s82, 13
	s_and_b32 s83, s81, 31
	s_mul_i32 s83, s83, 0xc00000
	s_add_i32 s82, s82, s83
	s_cmp_lt_u32 s81, 32
	s_cselect_b32 s88, s92, s94
	s_cselect_b32 s89, s93, s95
	s_mov_b32 s83, 0x1f210000
	s_cselect_b32 s83, 0x7210000, s83
	s_add_u32 s88, s88, s82
	s_addc_u32 s89, s89, 0
	s_add_u32 s88, s88, 0xc000
	s_addc_u32 s89, s89, 0
	s_add_u32 s83, s83, s82
	s_add_u32 s90, s98, s83
	s_addc_u32 s91, s99, 0
	global_load_dwordx4 v[64:67], v22, s[84:85] nt
	global_load_dwordx4 v[68:71], v22, s[84:85] offset:1024 nt
	global_load_dwordx4 v[72:75], v22, s[84:85] offset:2048 nt
	global_load_dwordx4 v[76:79], v22, s[84:85] offset:3072 nt
	global_load_dwordx4 v[80:83], v23, s[84:85] nt
	global_load_dwordx4 v[84:87], v23, s[84:85] offset:1024 nt
	global_load_dwordx4 v[88:91], v23, s[84:85] offset:2048 nt
	global_load_dwordx4 v[92:95], v23, s[84:85] offset:3072 nt
	global_load_dwordx4 v[96:99], v22, s[88:89] nt
	global_load_dwordx4 v[100:103], v22, s[88:89] offset:1024 nt
	global_load_dwordx4 v[104:107], v22, s[88:89] offset:2048 nt
	global_load_dwordx4 v[108:111], v22, s[88:89] offset:3072 nt
	global_load_dwordx4 v[112:115], v23, s[88:89] nt
	global_load_dwordx4 v[116:119], v23, s[88:89] offset:1024 nt
	global_load_dwordx4 v[120:123], v23, s[88:89] offset:2048 nt
	global_load_dwordx4 v[124:127], v23, s[88:89] offset:3072 nt
	s_waitcnt vmcnt(15)
	global_store_dwordx4 v22, v[64:67], s[86:87] nt
	s_waitcnt vmcnt(15)
	global_store_dwordx4 v22, v[68:71], s[86:87] offset:1024 nt
	s_waitcnt vmcnt(15)
	global_store_dwordx4 v22, v[72:75], s[86:87] offset:2048 nt
	s_waitcnt vmcnt(15)
	global_store_dwordx4 v22, v[76:79], s[86:87] offset:3072 nt
	s_waitcnt vmcnt(15)
	global_store_dwordx4 v23, v[80:83], s[86:87] nt
	s_waitcnt vmcnt(15)
	global_store_dwordx4 v23, v[84:87], s[86:87] offset:1024 nt
	s_waitcnt vmcnt(15)
	global_store_dwordx4 v23, v[88:91], s[86:87] offset:2048 nt
	s_waitcnt vmcnt(15)
	global_store_dwordx4 v23, v[92:95], s[86:87] offset:3072 nt
	s_waitcnt vmcnt(15)
	global_store_dwordx4 v22, v[96:99], s[90:91] nt
	s_waitcnt vmcnt(15)
	global_store_dwordx4 v22, v[100:103], s[90:91] offset:1024 nt
	s_waitcnt vmcnt(15)
	global_store_dwordx4 v22, v[104:107], s[90:91] offset:2048 nt
	s_waitcnt vmcnt(15)
	global_store_dwordx4 v22, v[108:111], s[90:91] offset:3072 nt
	s_waitcnt vmcnt(15)
	global_store_dwordx4 v23, v[112:115], s[90:91] nt
	s_waitcnt vmcnt(15)
	global_store_dwordx4 v23, v[116:119], s[90:91] offset:1024 nt
	s_waitcnt vmcnt(15)
	global_store_dwordx4 v23, v[120:123], s[90:91] offset:2048 nt
	s_waitcnt vmcnt(15)
	global_store_dwordx4 v23, v[124:127], s[90:91] offset:3072 nt
	s_add_i32 s80, s101, s100
	s_branch .Lcpyfp_loop
.Lcpyfp_tail:
	s_cmp_lt_u32 s80, 0xcb6e
	s_cbranch_scc0 .Lcpyfp_end
	s_mul_hi_u32 s81, s80, 0x2ad5802b
	s_lshr_b32 s81, s81, 8
	s_mul_i32 s82, s81, 0x5fa
	s_sub_i32 s82, s80, s82
	s_lshl_b32 s82, s82, 13
	s_and_b32 s83, s81, 31
	s_mul_i32 s83, s83, 0xc00000
	s_add_i32 s82, s82, s83
	s_cmp_lt_u32 s81, 32
	s_cselect_b32 s84, s92, s94
	s_cselect_b32 s85, s93, s95
	s_mov_b32 s83, 0x1f210000
	s_cselect_b32 s83, 0x7210000, s83
	s_add_u32 s84, s84, s82
	s_addc_u32 s85, s85, 0
	s_add_u32 s84, s84, 0xc000
	s_addc_u32 s85, s85, 0
	s_add_u32 s83, s83, s82
	s_add_u32 s86, s98, s83
	s_addc_u32 s87, s99, 0
	global_load_dwordx4 v[64:67], v22, s[84:85] nt
	global_load_dwordx4 v[68:71], v22, s[84:85] offset:1024 nt
	global_load_dwordx4 v[72:75], v22, s[84:85] offset:2048 nt
	global_load_dwordx4 v[76:79], v22, s[84:85] offset:3072 nt
	global_load_dwordx4 v[80:83], v23, s[84:85] nt
	global_load_dwordx4 v[84:87], v23, s[84:85] offset:1024 nt
	global_load_dwordx4 v[88:91], v23, s[84:85] offset:2048 nt
	global_load_dwordx4 v[92:95], v23, s[84:85] offset:3072 nt
	s_waitcnt vmcnt(7)
	global_store_dwordx4 v22, v[64:67], s[86:87] nt
	s_waitcnt vmcnt(7)
	global_store_dwordx4 v22, v[68:71], s[86:87] offset:1024 nt
	s_waitcnt vmcnt(7)
	global_store_dwordx4 v22, v[72:75], s[86:87] offset:2048 nt
	s_waitcnt vmcnt(7)
	global_store_dwordx4 v22, v[76:79], s[86:87] offset:3072 nt
	s_waitcnt vmcnt(7)
	global_store_dwordx4 v23, v[80:83], s[86:87] nt
	s_waitcnt vmcnt(7)
	global_store_dwordx4 v23, v[84:87], s[86:87] offset:1024 nt
	s_waitcnt vmcnt(7)
	global_store_dwordx4 v23, v[88:91], s[86:87] offset:2048 nt
	s_waitcnt vmcnt(7)
	global_store_dwordx4 v23, v[92:95], s[86:87] offset:3072 nt

.Lmgf_end:
	v_lshrrev_b32_e32 v21, 6, v174
	v_and_b32_e32 v22, 63, v174
	v_lshlrev_b32_e32 v22, 4, v22
	v_readfirstlane_b32 s80, v21
	v_add_u32_e32 v23, 0x1000, v22
	v_readfirstlane_b32 s92, v235
	v_readfirstlane_b32 s93, v236
	v_readfirstlane_b32 s94, v237
	v_readfirstlane_b32 s95, v238
	v_readfirstlane_b32 s98, v239
	v_readfirstlane_b32 s99, v240
	s_lshr_b32 s100, s33, 7
	s_lshl_b32 s100, s100, 3
	s_lshr_b32 s101, s33, 3
	s_and_b32 s101, s101, 7
	s_add_i32 s100, s100, s101
	s_lshl_b32 s100, s100, 3
	s_add_i32 s80, s80, s100
	s_add_i32 s80, s80, 0xcb6e
	s_movk_i32 s100, 0x400
.Lcpyf_loop:
	s_add_i32 s101, s80, s100
	s_cmp_lt_u32 s101, 0xd050
	s_cbranch_scc0 .Lcpyf_tail
	s_mul_hi_u32 s81, s80, 0x2ad5802b
	s_lshr_b32 s81, s81, 8
	s_mul_i32 s82, s81, 0x5fa
	s_sub_i32 s82, s80, s82
	s_lshl_b32 s82, s82, 13
	s_and_b32 s83, s81, 31
	s_mul_i32 s83, s83, 0xc00000
	s_add_i32 s82, s82, s83
	s_cmp_lt_u32 s81, 32
	s_cselect_b32 s84, s92, s94
	s_cselect_b32 s85, s93, s95
	s_mov_b32 s83, 0x1f210000
	s_cselect_b32 s83, 0x7210000, s83
	s_add_u32 s84, s84, s82
	s_addc_u32 s85, s85, 0
	s_add_u32 s84, s84, 0xc000
	s_addc_u32 s85, s85, 0
	s_add_u32 s83, s83, s82
	s_add_u32 s86, s98, s83
	s_addc_u32 s87, s99, 0
	s_mul_hi_u32 s81, s101, 0x2ad5802b
	s_lshr_b32 s81, s81, 8
	s_mul_i32 s82, s81, 0x5fa
	s_sub_i32 s82, s101, s82
	s_lshl_b32 s82, s82, 13
	s_and_b32 s83, s81, 31
	s_mul_i32 s83, s83, 0xc00000
	s_add_i32 s82, s82, s83
	s_cmp_lt_u32 s81, 32
	s_cselect_b32 s88, s92, s94
	s_cselect_b32 s89, s93, s95
	s_mov_b32 s83, 0x1f210000
	s_cselect_b32 s83, 0x7210000, s83
	s_add_u32 s88, s88, s82
	s_addc_u32 s89, s89, 0
	s_add_u32 s88, s88, 0xc000
	s_addc_u32 s89, s89, 0
	s_add_u32 s83, s83, s82
	s_add_u32 s90, s98, s83
	s_addc_u32 s91, s99, 0
	global_load_dwordx4 v[64:67], v22, s[84:85] nt
	global_load_dwordx4 v[68:71], v22, s[84:85] offset:1024 nt
	global_load_dwordx4 v[72:75], v22, s[84:85] offset:2048 nt
	global_load_dwordx4 v[76:79], v22, s[84:85] offset:3072 nt
	global_load_dwordx4 v[80:83], v23, s[84:85] nt
	global_load_dwordx4 v[84:87], v23, s[84:85] offset:1024 nt
	global_load_dwordx4 v[88:91], v23, s[84:85] offset:2048 nt
	global_load_dwordx4 v[92:95], v23, s[84:85] offset:3072 nt
	global_load_dwordx4 v[96:99], v22, s[88:89] nt
	global_load_dwordx4 v[100:103], v22, s[88:89] offset:1024 nt
	global_load_dwordx4 v[104:107], v22, s[88:89] offset:2048 nt
	global_load_dwordx4 v[108:111], v22, s[88:89] offset:3072 nt
	global_load_dwordx4 v[112:115], v23, s[88:89] nt
	global_load_dwordx4 v[116:119], v23, s[88:89] offset:1024 nt
	global_load_dwordx4 v[120:123], v23, s[88:89] offset:2048 nt
	global_load_dwordx4 v[124:127], v23, s[88:89] offset:3072 nt
	s_waitcnt vmcnt(15)
	global_store_dwordx4 v22, v[64:67], s[86:87] nt
	s_waitcnt vmcnt(15)
	global_store_dwordx4 v22, v[68:71], s[86:87] offset:1024 nt
	s_waitcnt vmcnt(15)
	global_store_dwordx4 v22, v[72:75], s[86:87] offset:2048 nt
	s_waitcnt vmcnt(15)
	global_store_dwordx4 v22, v[76:79], s[86:87] offset:3072 nt
	s_waitcnt vmcnt(15)
	global_store_dwordx4 v23, v[80:83], s[86:87] nt
	s_waitcnt vmcnt(15)
	global_store_dwordx4 v23, v[84:87], s[86:87] offset:1024 nt
	s_waitcnt vmcnt(15)
	global_store_dwordx4 v23, v[88:91], s[86:87] offset:2048 nt
	s_waitcnt vmcnt(15)
	global_store_dwordx4 v23, v[92:95], s[86:87] offset:3072 nt
	s_waitcnt vmcnt(15)
	global_store_dwordx4 v22, v[96:99], s[90:91] nt
	s_waitcnt vmcnt(15)
	global_store_dwordx4 v22, v[100:103], s[90:91] offset:1024 nt
	s_waitcnt vmcnt(15)
	global_store_dwordx4 v22, v[104:107], s[90:91] offset:2048 nt
	s_waitcnt vmcnt(15)
	global_store_dwordx4 v22, v[108:111], s[90:91] offset:3072 nt
	s_waitcnt vmcnt(15)
	global_store_dwordx4 v23, v[112:115], s[90:91] nt
	s_waitcnt vmcnt(15)
	global_store_dwordx4 v23, v[116:119], s[90:91] offset:1024 nt
	s_waitcnt vmcnt(15)
	global_store_dwordx4 v23, v[120:123], s[90:91] offset:2048 nt
	s_waitcnt vmcnt(15)
	global_store_dwordx4 v23, v[124:127], s[90:91] offset:3072 nt
	s_add_i32 s80, s101, s100
	s_branch .Lcpyf_loop
.Lcpyf_tail:
	s_cmp_lt_u32 s80, 0xd050
	s_cbranch_scc0 .Lcpyf_end
	s_mul_hi_u32 s81, s80, 0x2ad5802b
	s_lshr_b32 s81, s81, 8
	s_mul_i32 s82, s81, 0x5fa
	s_sub_i32 s82, s80, s82
	s_lshl_b32 s82, s82, 13
	s_and_b32 s83, s81, 31
	s_mul_i32 s83, s83, 0xc00000
	s_add_i32 s82, s82, s83
	s_cmp_lt_u32 s81, 32
	s_cselect_b32 s84, s92, s94
	s_cselect_b32 s85, s93, s95
	s_mov_b32 s83, 0x1f210000
	s_cselect_b32 s83, 0x7210000, s83
	s_add_u32 s84, s84, s82
	s_addc_u32 s85, s85, 0
	s_add_u32 s84, s84, 0xc000
	s_addc_u32 s85, s85, 0
	s_add_u32 s83, s83, s82
	s_add_u32 s86, s98, s83
	s_addc_u32 s87, s99, 0
	global_load_dwordx4 v[64:67], v22, s[84:85] nt
	global_load_dwordx4 v[68:71], v22, s[84:85] offset:1024 nt
	global_load_dwordx4 v[72:75], v22, s[84:85] offset:2048 nt
	global_load_dwordx4 v[76:79], v22, s[84:85] offset:3072 nt
	global_load_dwordx4 v[80:83], v23, s[84:85] nt
	global_load_dwordx4 v[84:87], v23, s[84:85] offset:1024 nt
	global_load_dwordx4 v[88:91], v23, s[84:85] offset:2048 nt
	global_load_dwordx4 v[92:95], v23, s[84:85] offset:3072 nt
	s_waitcnt vmcnt(7)
	global_store_dwordx4 v22, v[64:67], s[86:87] nt
	s_waitcnt vmcnt(7)
	global_store_dwordx4 v22, v[68:71], s[86:87] offset:1024 nt
	s_waitcnt vmcnt(7)
	global_store_dwordx4 v22, v[72:75], s[86:87] offset:2048 nt
	s_waitcnt vmcnt(7)
	global_store_dwordx4 v22, v[76:79], s[86:87] offset:3072 nt
	s_waitcnt vmcnt(7)
	global_store_dwordx4 v23, v[80:83], s[86:87] nt
	s_waitcnt vmcnt(7)
	global_store_dwordx4 v23, v[84:87], s[86:87] offset:1024 nt
	s_waitcnt vmcnt(7)
	global_store_dwordx4 v23, v[88:91], s[86:87] offset:2048 nt
	s_waitcnt vmcnt(7)
	global_store_dwordx4 v23, v[92:95], s[86:87] offset:3072 nt

.LBB0_1461:
	s_cmp_lt_u32 s33, 1200
	s_cbranch_scc1 .Lcpyg_end
	v_lshrrev_b32_e32 v21, 6, v174
	v_and_b32_e32 v22, 63, v174
	v_lshlrev_b32_e32 v22, 4, v22
	v_readfirstlane_b32 s80, v21
	v_add_u32_e32 v23, 0x1000, v22
	v_readfirstlane_b32 s92, v235
	v_readfirstlane_b32 s93, v236
	v_readfirstlane_b32 s94, v237
	v_readfirstlane_b32 s95, v238
	v_readfirstlane_b32 s98, v239
	v_readfirstlane_b32 s99, v240
	s_add_i32 s80, s80, s33
	s_add_i32 s80, s80, 0xcba0
	s_sub_i32 s100, s78, 150
	s_lshl_b32 s100, s100, 3
.Lcpyg_loop:
	s_add_i32 s101, s80, s100
	s_cmp_lt_u32 s101, 0xef90
	s_cbranch_scc0 .Lcpyg_tail
	s_mul_hi_u32 s81, s80, 0x2ad5802b
	s_lshr_b32 s81, s81, 8
	s_mul_i32 s82, s81, 0x5fa
	s_sub_i32 s82, s80, s82
	s_lshl_b32 s82, s82, 13
	s_and_b32 s83, s81, 31
	s_mul_i32 s83, s83, 0xc00000
	s_add_i32 s82, s82, s83
	s_cmp_lt_u32 s81, 32
	s_cselect_b32 s84, s92, s94
	s_cselect_b32 s85, s93, s95
	s_mov_b32 s83, 0x1f210000
	s_cselect_b32 s83, 0x7210000, s83
	s_add_u32 s84, s84, s82
	s_addc_u32 s85, s85, 0
	s_add_u32 s84, s84, 0xc000
	s_addc_u32 s85, s85, 0
	s_add_u32 s83, s83, s82
	s_add_u32 s86, s98, s83
	s_addc_u32 s87, s99, 0
	s_mul_hi_u32 s81, s101, 0x2ad5802b
	s_lshr_b32 s81, s81, 8
	s_mul_i32 s82, s81, 0x5fa
	s_sub_i32 s82, s101, s82
	s_lshl_b32 s82, s82, 13
	s_and_b32 s83, s81, 31
	s_mul_i32 s83, s83, 0xc00000
	s_add_i32 s82, s82, s83
	s_cmp_lt_u32 s81, 32
	s_cselect_b32 s88, s92, s94
	s_cselect_b32 s89, s93, s95
	s_mov_b32 s83, 0x1f210000
	s_cselect_b32 s83, 0x7210000, s83
	s_add_u32 s88, s88, s82
	s_addc_u32 s89, s89, 0
	s_add_u32 s88, s88, 0xc000
	s_addc_u32 s89, s89, 0
	s_add_u32 s83, s83, s82
	s_add_u32 s90, s98, s83
	s_addc_u32 s91, s99, 0
	global_load_dwordx4 v[64:67], v22, s[84:85] nt
	global_load_dwordx4 v[68:71], v22, s[84:85] offset:1024 nt
	global_load_dwordx4 v[72:75], v22, s[84:85] offset:2048 nt
	global_load_dwordx4 v[76:79], v22, s[84:85] offset:3072 nt
	global_load_dwordx4 v[80:83], v23, s[84:85] nt
	global_load_dwordx4 v[84:87], v23, s[84:85] offset:1024 nt
	global_load_dwordx4 v[88:91], v23, s[84:85] offset:2048 nt
	global_load_dwordx4 v[92:95], v23, s[84:85] offset:3072 nt
	global_load_dwordx4 v[96:99], v22, s[88:89] nt
	global_load_dwordx4 v[100:103], v22, s[88:89] offset:1024 nt
	global_load_dwordx4 v[104:107], v22, s[88:89] offset:2048 nt
	global_load_dwordx4 v[108:111], v22, s[88:89] offset:3072 nt
	global_load_dwordx4 v[112:115], v23, s[88:89] nt
	global_load_dwordx4 v[116:119], v23, s[88:89] offset:1024 nt
	global_load_dwordx4 v[120:123], v23, s[88:89] offset:2048 nt
	global_load_dwordx4 v[124:127], v23, s[88:89] offset:3072 nt
	s_waitcnt vmcnt(15)
	global_store_dwordx4 v22, v[64:67], s[86:87] nt
	s_waitcnt vmcnt(15)
	global_store_dwordx4 v22, v[68:71], s[86:87] offset:1024 nt
	s_waitcnt vmcnt(15)
	global_store_dwordx4 v22, v[72:75], s[86:87] offset:2048 nt
	s_waitcnt vmcnt(15)
	global_store_dwordx4 v22, v[76:79], s[86:87] offset:3072 nt
	s_waitcnt vmcnt(15)
	global_store_dwordx4 v23, v[80:83], s[86:87] nt
	s_waitcnt vmcnt(15)
	global_store_dwordx4 v23, v[84:87], s[86:87] offset:1024 nt
	s_waitcnt vmcnt(15)
	global_store_dwordx4 v23, v[88:91], s[86:87] offset:2048 nt
	s_waitcnt vmcnt(15)
	global_store_dwordx4 v23, v[92:95], s[86:87] offset:3072 nt
	s_waitcnt vmcnt(15)
	global_store_dwordx4 v22, v[96:99], s[90:91] nt
	s_waitcnt vmcnt(15)
	global_store_dwordx4 v22, v[100:103], s[90:91] offset:1024 nt
	s_waitcnt vmcnt(15)
	global_store_dwordx4 v22, v[104:107], s[90:91] offset:2048 nt
	s_waitcnt vmcnt(15)
	global_store_dwordx4 v22, v[108:111], s[90:91] offset:3072 nt
	s_waitcnt vmcnt(15)
	global_store_dwordx4 v23, v[112:115], s[90:91] nt
	s_waitcnt vmcnt(15)
	global_store_dwordx4 v23, v[116:119], s[90:91] offset:1024 nt
	s_waitcnt vmcnt(15)
	global_store_dwordx4 v23, v[120:123], s[90:91] offset:2048 nt
	s_waitcnt vmcnt(15)
	global_store_dwordx4 v23, v[124:127], s[90:91] offset:3072 nt
	s_add_i32 s80, s101, s100
	s_branch .Lcpyg_loop
.Lcpyg_tail:
	s_cmp_lt_u32 s80, 0xef90
	s_cbranch_scc0 .Lcpyg_end
	s_mul_hi_u32 s81, s80, 0x2ad5802b
	s_lshr_b32 s81, s81, 8
	s_mul_i32 s82, s81, 0x5fa
	s_sub_i32 s82, s80, s82
	s_lshl_b32 s82, s82, 13
	s_and_b32 s83, s81, 31
	s_mul_i32 s83, s83, 0xc00000
	s_add_i32 s82, s82, s83
	s_cmp_lt_u32 s81, 32
	s_cselect_b32 s84, s92, s94
	s_cselect_b32 s85, s93, s95
	s_mov_b32 s83, 0x1f210000
	s_cselect_b32 s83, 0x7210000, s83
	s_add_u32 s84, s84, s82
	s_addc_u32 s85, s85, 0
	s_add_u32 s84, s84, 0xc000
	s_addc_u32 s85, s85, 0
	s_add_u32 s83, s83, s82
	s_add_u32 s86, s98, s83
	s_addc_u32 s87, s99, 0
	global_load_dwordx4 v[64:67], v22, s[84:85] nt
	global_load_dwordx4 v[68:71], v22, s[84:85] offset:1024 nt
	global_load_dwordx4 v[72:75], v22, s[84:85] offset:2048 nt
	global_load_dwordx4 v[76:79], v22, s[84:85] offset:3072 nt
	global_load_dwordx4 v[80:83], v23, s[84:85] nt
	global_load_dwordx4 v[84:87], v23, s[84:85] offset:1024 nt
	global_load_dwordx4 v[88:91], v23, s[84:85] offset:2048 nt
	global_load_dwordx4 v[92:95], v23, s[84:85] offset:3072 nt
	s_waitcnt vmcnt(7)
	global_store_dwordx4 v22, v[64:67], s[86:87] nt
	s_waitcnt vmcnt(7)
	global_store_dwordx4 v22, v[68:71], s[86:87] offset:1024 nt
	s_waitcnt vmcnt(7)
	global_store_dwordx4 v22, v[72:75], s[86:87] offset:2048 nt
	s_waitcnt vmcnt(7)
	global_store_dwordx4 v22, v[76:79], s[86:87] offset:3072 nt
	s_waitcnt vmcnt(7)
	global_store_dwordx4 v23, v[80:83], s[86:87] nt
	s_waitcnt vmcnt(7)
	global_store_dwordx4 v23, v[84:87], s[86:87] offset:1024 nt
	s_waitcnt vmcnt(7)
	global_store_dwordx4 v23, v[88:91], s[86:87] offset:2048 nt
	s_waitcnt vmcnt(7)
	global_store_dwordx4 v23, v[92:95], s[86:87] offset:3072 nt

.LBB0_1481:
	s_or_b64 exec, exec, s[6:7]
	v_readlane_b32 s4, v234, 2
	v_mov_b32_e32 v8, v174
	v_readlane_b32 s5, v234, 3
	s_barrier
	s_and_b32 s80, s33, 64
	s_cmp_eq_u32 s80, 0
	s_cbranch_scc1 .Lpre4_skip
	v_lshrrev_b32_e32 v21, 6, v174
	v_and_b32_e32 v22, 63, v174
	v_lshlrev_b32_e32 v22, 4, v22
	v_readfirstlane_b32 s80, v21
	v_add_u32_e32 v23, 0x1000, v22
	v_readfirstlane_b32 s92, v235
	v_readfirstlane_b32 s93, v236
	v_readfirstlane_b32 s94, v237
	v_readfirstlane_b32 s95, v238
	v_readfirstlane_b32 s98, v239
	v_readfirstlane_b32 s99, v240
	s_lshr_b32 s100, s33, 7
	s_lshl_b32 s100, s100, 3
	s_lshr_b32 s101, s33, 3
	s_and_b32 s101, s101, 7
	s_add_i32 s100, s100, s101
	s_lshl_b32 s100, s100, 3
	s_add_i32 s80, s80, s100
	s_add_i32 s80, s80, 0xef90
	s_movk_i32 s100, 0x400
.Lcpy4p_loop:
	s_add_i32 s101, s80, s100
	s_cmp_lt_u32 s101, 0xf4c4
	s_cbranch_scc0 .Lcpy4p_tail
	s_mul_hi_u32 s81, s80, 0x2ad5802b
	s_lshr_b32 s81, s81, 8
	s_mul_i32 s82, s81, 0x5fa
	s_sub_i32 s82, s80, s82
	s_lshl_b32 s82, s82, 13
	s_and_b32 s83, s81, 31
	s_mul_i32 s83, s83, 0xc00000
	s_add_i32 s82, s82, s83
	s_cmp_lt_u32 s81, 32
	s_cselect_b32 s84, s92, s94
	s_cselect_b32 s85, s93, s95
	s_mov_b32 s83, 0x1f210000
	s_cselect_b32 s83, 0x7210000, s83
	s_add_u32 s84, s84, s82
	s_addc_u32 s85, s85, 0
	s_add_u32 s84, s84, 0xc000
	s_addc_u32 s85, s85, 0
	s_add_u32 s83, s83, s82
	s_add_u32 s86, s98, s83
	s_addc_u32 s87, s99, 0
	s_mul_hi_u32 s81, s101, 0x2ad5802b
	s_lshr_b32 s81, s81, 8
	s_mul_i32 s82, s81, 0x5fa
	s_sub_i32 s82, s101, s82
	s_lshl_b32 s82, s82, 13
	s_and_b32 s83, s81, 31
	s_mul_i32 s83, s83, 0xc00000
	s_add_i32 s82, s82, s83
	s_cmp_lt_u32 s81, 32
	s_cselect_b32 s88, s92, s94
	s_cselect_b32 s89, s93, s95
	s_mov_b32 s83, 0x1f210000
	s_cselect_b32 s83, 0x7210000, s83
	s_add_u32 s88, s88, s82
	s_addc_u32 s89, s89, 0
	s_add_u32 s88, s88, 0xc000
	s_addc_u32 s89, s89, 0
	s_add_u32 s83, s83, s82
	s_add_u32 s90, s98, s83
	s_addc_u32 s91, s99, 0
	global_load_dwordx4 v[64:67], v22, s[84:85] nt
	global_load_dwordx4 v[68:71], v22, s[84:85] offset:1024 nt
	global_load_dwordx4 v[72:75], v22, s[84:85] offset:2048 nt
	global_load_dwordx4 v[76:79], v22, s[84:85] offset:3072 nt
	global_load_dwordx4 v[80:83], v23, s[84:85] nt
	global_load_dwordx4 v[84:87], v23, s[84:85] offset:1024 nt
	global_load_dwordx4 v[88:91], v23, s[84:85] offset:2048 nt
	global_load_dwordx4 v[92:95], v23, s[84:85] offset:3072 nt
	global_load_dwordx4 v[96:99], v22, s[88:89] nt
	global_load_dwordx4 v[100:103], v22, s[88:89] offset:1024 nt
	global_load_dwordx4 v[104:107], v22, s[88:89] offset:2048 nt
	global_load_dwordx4 v[108:111], v22, s[88:89] offset:3072 nt
	global_load_dwordx4 v[112:115], v23, s[88:89] nt
	global_load_dwordx4 v[116:119], v23, s[88:89] offset:1024 nt
	global_load_dwordx4 v[120:123], v23, s[88:89] offset:2048 nt
	global_load_dwordx4 v[124:127], v23, s[88:89] offset:3072 nt
	s_waitcnt vmcnt(15)
	global_store_dwordx4 v22, v[64:67], s[86:87] nt
	s_waitcnt vmcnt(15)
	global_store_dwordx4 v22, v[68:71], s[86:87] offset:1024 nt
	s_waitcnt vmcnt(15)
	global_store_dwordx4 v22, v[72:75], s[86:87] offset:2048 nt
	s_waitcnt vmcnt(15)
	global_store_dwordx4 v22, v[76:79], s[86:87] offset:3072 nt
	s_waitcnt vmcnt(15)
	global_store_dwordx4 v23, v[80:83], s[86:87] nt
	s_waitcnt vmcnt(15)
	global_store_dwordx4 v23, v[84:87], s[86:87] offset:1024 nt
	s_waitcnt vmcnt(15)
	global_store_dwordx4 v23, v[88:91], s[86:87] offset:2048 nt
	s_waitcnt vmcnt(15)
	global_store_dwordx4 v23, v[92:95], s[86:87] offset:3072 nt
	s_waitcnt vmcnt(15)
	global_store_dwordx4 v22, v[96:99], s[90:91] nt
	s_waitcnt vmcnt(15)
	global_store_dwordx4 v22, v[100:103], s[90:91] offset:1024 nt
	s_waitcnt vmcnt(15)
	global_store_dwordx4 v22, v[104:107], s[90:91] offset:2048 nt
	s_waitcnt vmcnt(15)
	global_store_dwordx4 v22, v[108:111], s[90:91] offset:3072 nt
	s_waitcnt vmcnt(15)
	global_store_dwordx4 v23, v[112:115], s[90:91] nt
	s_waitcnt vmcnt(15)
	global_store_dwordx4 v23, v[116:119], s[90:91] offset:1024 nt
	s_waitcnt vmcnt(15)
	global_store_dwordx4 v23, v[120:123], s[90:91] offset:2048 nt
	s_waitcnt vmcnt(15)
	global_store_dwordx4 v23, v[124:127], s[90:91] offset:3072 nt
	s_add_i32 s80, s101, s100
	s_branch .Lcpy4p_loop
.Lcpy4p_tail:
	s_cmp_lt_u32 s80, 0xf4c4
	s_cbranch_scc0 .Lcpy4p_end
	s_mul_hi_u32 s81, s80, 0x2ad5802b
	s_lshr_b32 s81, s81, 8
	s_mul_i32 s82, s81, 0x5fa
	s_sub_i32 s82, s80, s82
	s_lshl_b32 s82, s82, 13
	s_and_b32 s83, s81, 31
	s_mul_i32 s83, s83, 0xc00000
	s_add_i32 s82, s82, s83
	s_cmp_lt_u32 s81, 32
	s_cselect_b32 s84, s92, s94
	s_cselect_b32 s85, s93, s95
	s_mov_b32 s83, 0x1f210000
	s_cselect_b32 s83, 0x7210000, s83
	s_add_u32 s84, s84, s82
	s_addc_u32 s85, s85, 0
	s_add_u32 s84, s84, 0xc000
	s_addc_u32 s85, s85, 0
	s_add_u32 s83, s83, s82
	s_add_u32 s86, s98, s83
	s_addc_u32 s87, s99, 0
	global_load_dwordx4 v[64:67], v22, s[84:85] nt
	global_load_dwordx4 v[68:71], v22, s[84:85] offset:1024 nt
	global_load_dwordx4 v[72:75], v22, s[84:85] offset:2048 nt
	global_load_dwordx4 v[76:79], v22, s[84:85] offset:3072 nt
	global_load_dwordx4 v[80:83], v23, s[84:85] nt
	global_load_dwordx4 v[84:87], v23, s[84:85] offset:1024 nt
	global_load_dwordx4 v[88:91], v23, s[84:85] offset:2048 nt
	global_load_dwordx4 v[92:95], v23, s[84:85] offset:3072 nt
	s_waitcnt vmcnt(7)
	global_store_dwordx4 v22, v[64:67], s[86:87] nt
	s_waitcnt vmcnt(7)
	global_store_dwordx4 v22, v[68:71], s[86:87] offset:1024 nt
	s_waitcnt vmcnt(7)
	global_store_dwordx4 v22, v[72:75], s[86:87] offset:2048 nt
	s_waitcnt vmcnt(7)
	global_store_dwordx4 v22, v[76:79], s[86:87] offset:3072 nt
	s_waitcnt vmcnt(7)
	global_store_dwordx4 v23, v[80:83], s[86:87] nt
	s_waitcnt vmcnt(7)
	global_store_dwordx4 v23, v[84:87], s[86:87] offset:1024 nt
	s_waitcnt vmcnt(7)
	global_store_dwordx4 v23, v[88:91], s[86:87] offset:2048 nt
	s_waitcnt vmcnt(7)
	global_store_dwordx4 v23, v[92:95], s[86:87] offset:3072 nt

.Lmg4_end:
	v_lshrrev_b32_e32 v21, 6, v174
	v_and_b32_e32 v22, 63, v174
	v_lshlrev_b32_e32 v22, 4, v22
	v_readfirstlane_b32 s80, v21
	v_add_u32_e32 v23, 0x1000, v22
	v_readfirstlane_b32 s92, v235
	v_readfirstlane_b32 s93, v236
	v_readfirstlane_b32 s94, v237
	v_readfirstlane_b32 s95, v238
	v_readfirstlane_b32 s98, v239
	v_readfirstlane_b32 s99, v240
	s_lshr_b32 s100, s33, 7
	s_lshl_b32 s100, s100, 3
	s_lshr_b32 s101, s33, 3
	s_and_b32 s101, s101, 7
	s_add_i32 s100, s100, s101
	s_lshl_b32 s100, s100, 3
	s_add_i32 s80, s80, s100
	s_add_i32 s80, s80, 0xf4c4
	s_movk_i32 s100, 0x400
